# row-ss loads issued before each tile K-loop (peeled first iteration, first wait vmcnt16); SwiGLU and in-proj epilogues have no vmcnt wait (on v32)
# speedup vs baseline: 1.0030x; 1.0030x over previous
; #define PG8_STAGE(bufoff, gbase, voff) do { _Pragma("unroll") for (int _i = 0; _i < 2; ++_i) \
;         __builtin_amdgcn_global_load_lds((const unsigned*)((const char*)(gbase) + (voff)[_i]), (LAS unsigned*)(lds + (bufoff) + ldsw + _i * 8192), 16, 0, 0); } while (0)
; #define PG8_LDA(dst, b, h) do { _Pragma("unroll") for (int m = 0; m < 4; ++m) _Pragma("unroll") for (int k = 0; k < 2; ++k) dst[m][k] = *(const LAS bf16x8*)(lds + PG8_SA(b, h) + aoff + m * 2048 + k * 1024); } while (0)
; #define PG8_LDB(dst, b, h) do { _Pragma("unroll") for (int n = 0; n < 2; ++n) _Pragma("unroll") for (int k = 0; k < 2; ++k) dst[n][k] = *(const LAS bf16x8*)(lds + PG8_SB(b, h) + boff + n * 2048 + k * 1024); } while (0)
; #define PG8_WAIT_V(n) asm volatile("s_waitcnt vmcnt(" #n ")" ::: "memory")
; #define PG8_WAIT_L(n) asm volatile("s_waitcnt lgkmcnt(" #n ")" ::: "memory")
; #define PG8_BAR __builtin_amdgcn_s_barrier()
; template <class Epi>
; __device__ __forceinline__ void gemm_phase(LAS unsigned char* lds, const Gemm g, const StaticOrder& S, const Epi& E) {
;     ...
;         const bool has_next = S.next(ui + 1, nxt);
;         const char* nA = has_next ? (const char*)g.A + (size_t)nxt.pm * tsA : cA; const char* nB = has_next ? (const char*)g.Bt + (size_t)nxt.pn * tsB : cB;
;         for (int t = 0; t < nt; t += 2) {
;             const bool last = (t == nt - 2);
;             const char* a1 = cA + (size_t)(t + 1) * kstep;
;             const char* a2 = last ? nA : cA + (size_t)(t + 2) * kstep; const char* b2 = last ? nB : cB + (size_t)(t + 2) * kstep;
;             const char* a3 = a2 + kstep; const char* b3 = b2 + kstep;
;             PG8_LDB(B0, 0, 0); PG8_LDB(B1, 0, 1); PG8_SCHED; PG8_LDA(At, 0, 0); PG8_STAGE(PG8_SA(1, 1), a1 + hsA, voffA);
;             PG8_WAIT_V(8); PG8_WAIT_L(0); PG8_BAR; PG8_MMA(0, 0, At, B0); PG8_MMA(0, 1, At, B1); PG8_BAR; PG8_SCHED;
;             PG8_LDA(At, 0, 1); PG8_STAGE(PG8_SB(0, 0), b2, voffB); PG8_STAGE(PG8_SB(0, 1), b2 + hsB, voffB); PG8_STAGE(PG8_SA(0, 0), a2, voffA);
;             PG8_WAIT_V(8); PG8_WAIT_L(0); PG8_BAR; PG8_MMA(1, 0, At, B0); PG8_MMA(1, 1, At, B1); PG8_BAR; PG8_SCHED;
;     __device__ __forceinline__ void operator()(const AccT& acc, const Unit& u, int wr, int wc, int fr, int fq) const {
;     ...
;                 const int row = row0 + ai * HALF + m * 16;
;                 const float rs = rsqrtf(ss[row] * (1.f / 1024.f) + EPS);
.LBB0_222:
	s_ashr_i32 s17, s16, 31
	s_lshl_b64 s[18:19], s[16:17], 19
	s_add_u32 s18, s46, s18
	s_addc_u32 s19, s47, s19
	s_and_b64 s[20:21], s[0:1], exec
	s_cselect_b32 s17, s19, s23
	s_cselect_b32 s80, s18, s22
	s_ashr_i32 s15, s14, 31
	s_lshl_b64 s[20:21], s[14:15], 19
	s_add_u32 s20, s34, s20
	s_addc_u32 s21, s35, s21
	s_and_b64 s[28:29], s[0:1], exec
	s_cselect_b32 s15, s21, s25
	s_cselect_b32 s81, s20, s24
	s_add_u32 s22, s22, 0x40080
	s_addc_u32 s23, s23, 0
	s_add_u32 s83, s24, 0x100
	s_addc_u32 s84, s25, 0
	s_mov_b32 s85, -2
	v_lshl_add_u32 v240, s4, 8, v129
	v_ashrrev_i32_e32 v241, 31, v240
	v_lshl_add_u64 v[242:243], v[240:241], 2, s[70:71]
	global_load_dword v232, v[242:243], off
	global_load_dword v233, v[242:243], off offset:64
	global_load_dword v234, v[242:243], off offset:128
	global_load_dword v235, v[242:243], off offset:192
	global_load_dword v236, v[242:243], off offset:512
	global_load_dword v237, v[242:243], off offset:576
	global_load_dword v238, v[242:243], off offset:640
	global_load_dword v239, v[242:243], off offset:704
	ds_read_b128 v[146:149], v152
	ds_read_b128 v[158:161], v152 offset:1024
	ds_read_b128 v[166:169], v152 offset:2048
	ds_read_b128 v[170:173], v152 offset:3072
	ds_read_b128 v[174:177], v153
	ds_read_b128 v[178:181], v153 offset:1024
	ds_read_b128 v[182:185], v153 offset:2048
	ds_read_b128 v[186:189], v153 offset:3072
	s_add_u32 s24, s22, 0xfffc0080
	s_addc_u32 s25, s23, -1
	s_cmp_eq_u32 s85, 12
	s_cselect_b32 s29, s17, s25
	s_cselect_b32 s28, s80, s24
	s_cselect_b32 s25, s15, s84
	s_cselect_b32 s24, s81, s83
	v_lshl_add_u64 v[222:223], s[22:23], 0, v[138:139]
	s_add_i32 m0, s59, 0xc000
	ds_read_b128 v[190:193], v154
	ds_read_b128 v[194:197], v154 offset:1024
	ds_read_b128 v[198:201], v154 offset:2048
	ds_read_b128 v[202:205], v154 offset:3072
	ds_read_b128 v[206:209], v154 offset:4096
	ds_read_b128 v[210:213], v154 offset:5120
	ds_read_b128 v[214:217], v154 offset:6144
	ds_read_b128 v[218:221], v154 offset:7168
	global_load_lds_dwordx4 v[222:223], off
	v_lshl_add_u64 v[222:223], s[22:23], 0, v[140:141]
	s_add_i32 m0, s59, 0xe000
	s_nop 0
	global_load_lds_dwordx4 v[222:223], off
	s_waitcnt vmcnt(16)
	s_waitcnt lgkmcnt(0)
	s_barrier
	s_setprio 1
	s_waitcnt lgkmcnt(0)
	v_mfma_f32_16x16x32_bf16 v[124:127], v[146:149], v[190:193], 0
	v_mfma_f32_16x16x32_bf16 v[120:123], v[166:169], v[190:193], 0
	v_mfma_f32_16x16x32_bf16 v[108:111], v[146:149], v[198:201], 0
	v_mfma_f32_16x16x32_bf16 v[104:107], v[166:169], v[198:201], 0
	v_mfma_f32_16x16x32_bf16 v[92:95], v[146:149], v[206:209], 0
	v_mfma_f32_16x16x32_bf16 v[88:91], v[166:169], v[206:209], 0
	v_mfma_f32_16x16x32_bf16 v[76:79], v[146:149], v[214:217], 0
	v_mfma_f32_16x16x32_bf16 v[72:75], v[166:169], v[214:217], 0
	v_mfma_f32_16x16x32_bf16 v[124:127], v[158:161], v[194:197], v[124:127]
	v_mfma_f32_16x16x32_bf16 v[120:123], v[170:173], v[194:197], v[120:123]
	v_mfma_f32_16x16x32_bf16 v[108:111], v[158:161], v[202:205], v[108:111]
	v_mfma_f32_16x16x32_bf16 v[104:107], v[170:173], v[202:205], v[104:107]
	v_mfma_f32_16x16x32_bf16 v[92:95], v[158:161], v[210:213], v[92:95]
	v_mfma_f32_16x16x32_bf16 v[88:91], v[170:173], v[210:213], v[88:91]
	v_mfma_f32_16x16x32_bf16 v[76:79], v[158:161], v[218:221], v[76:79]
	v_mfma_f32_16x16x32_bf16 v[72:75], v[170:173], v[218:221], v[72:75]
	s_setprio 0
	s_setprio 1
	v_mfma_f32_16x16x32_bf16 v[116:119], v[174:177], v[190:193], 0
	v_mfma_f32_16x16x32_bf16 v[112:115], v[182:185], v[190:193], 0
	v_mfma_f32_16x16x32_bf16 v[100:103], v[174:177], v[198:201], 0
	v_mfma_f32_16x16x32_bf16 v[96:99], v[182:185], v[198:201], 0
	v_mfma_f32_16x16x32_bf16 v[84:87], v[174:177], v[206:209], 0
	v_mfma_f32_16x16x32_bf16 v[80:83], v[182:185], v[206:209], 0
	v_mfma_f32_16x16x32_bf16 v[68:71], v[174:177], v[214:217], 0
	v_mfma_f32_16x16x32_bf16 v[64:67], v[182:185], v[214:217], 0
	v_mfma_f32_16x16x32_bf16 v[116:119], v[178:181], v[194:197], v[116:119]
	v_mfma_f32_16x16x32_bf16 v[112:115], v[186:189], v[194:197], v[112:115]
	v_mfma_f32_16x16x32_bf16 v[100:103], v[178:181], v[202:205], v[100:103]
	v_mfma_f32_16x16x32_bf16 v[96:99], v[186:189], v[202:205], v[96:99]
	v_mfma_f32_16x16x32_bf16 v[84:87], v[178:181], v[210:213], v[84:87]
	v_mfma_f32_16x16x32_bf16 v[80:83], v[186:189], v[210:213], v[80:83]
	v_mfma_f32_16x16x32_bf16 v[68:71], v[178:181], v[218:221], v[68:71]
	v_mfma_f32_16x16x32_bf16 v[64:67], v[186:189], v[218:221], v[64:67]
	s_setprio 0
	s_barrier
	s_add_i32 s33, s76, s56
	v_lshl_add_u64 v[222:223], s[24:25], 0, v[134:135]
	s_mov_b32 m0, s33
	ds_read_b128 v[190:193], v154 offset:16384
	ds_read_b128 v[194:197], v154 offset:17408
	ds_read_b128 v[198:201], v154 offset:18432
	ds_read_b128 v[202:205], v154 offset:19456
	ds_read_b128 v[206:209], v154 offset:20480
	ds_read_b128 v[210:213], v154 offset:21504
	ds_read_b128 v[214:217], v154 offset:22528
	ds_read_b128 v[218:221], v154 offset:23552
	global_load_lds_dwordx4 v[222:223], off
	s_add_i32 m0, s33, 0x2000
	s_add_u32 s86, s24, 0x40000
	v_lshl_add_u64 v[224:225], s[24:25], 0, v[130:131]
	s_addc_u32 s87, s25, 0
	s_add_i32 s33, s77, s56
	global_load_lds_dwordx4 v[224:225], off
	v_lshl_add_u64 v[226:227], s[86:87], 0, v[134:135]
	s_mov_b32 m0, s33
	v_lshl_add_u64 v[228:229], s[28:29], 0, v[132:133]
	global_load_lds_dwordx4 v[226:227], off
	v_lshl_add_u64 v[226:227], s[86:87], 0, v[130:131]
	s_add_i32 m0, s33, 0x2000
	s_nop 0
	global_load_lds_dwordx4 v[226:227], off
	v_lshl_add_u64 v[226:227], s[28:29], 0, v[136:137]
	s_mov_b32 m0, s59
	s_nop 0
	global_load_lds_dwordx4 v[226:227], off
	s_mov_b32 m0, s60
	s_nop 0
	global_load_lds_dwordx4 v[228:229], off
	s_waitcnt vmcnt(8)
	s_waitcnt lgkmcnt(0)
	s_barrier
; #define PG8_STAGE(bufoff, gbase, voff) do { _Pragma("unroll") for (int _i = 0; _i < 2; ++_i) \
;         __builtin_amdgcn_global_load_lds((const unsigned*)((const char*)(gbase) + (voff)[_i]), (LAS unsigned*)(lds + (bufoff) + ldsw + _i * 8192), 16, 0, 0); } while (0)
; #define PG8_LDA(dst, b, h) do { _Pragma("unroll") for (int m = 0; m < 4; ++m) _Pragma("unroll") for (int k = 0; k < 2; ++k) dst[m][k] = *(const LAS bf16x8*)(lds + PG8_SA(b, h) + aoff + m * 2048 + k * 1024); } while (0)
; #define PG8_LDB(dst, b, h) do { _Pragma("unroll") for (int n = 0; n < 2; ++n) _Pragma("unroll") for (int k = 0; k < 2; ++k) dst[n][k] = *(const LAS bf16x8*)(lds + PG8_SB(b, h) + boff + n * 2048 + k * 1024); } while (0)
; #define PG8_MMA(ai, bj, At, Bt) do { __builtin_amdgcn_s_setprio(1); _Pragma("unroll") for (int m = 0; m < 4; ++m) _Pragma("unroll") for (int n = 0; n < 2; ++n) _Pragma("unroll") for (int k = 0; k < 2; ++k) \
;         acc[ai][bj][m][n] = __builtin_amdgcn_mfma_f32_16x16x32_bf16(Bt[n][k], At[m][k], acc[ai][bj][m][n], 0, 0, 0); __builtin_amdgcn_s_setprio(0); } while (0)
; #define PG8_WAIT_V(n) asm volatile("s_waitcnt vmcnt(" #n ")" ::: "memory")
; #define PG8_WAIT_L(n) asm volatile("s_waitcnt lgkmcnt(" #n ")" ::: "memory")
; #define PG8_BAR __builtin_amdgcn_s_barrier()
; #define PG8_SCHED __builtin_amdgcn_sched_barrier(0)
; template <class Epi>
; __device__ __forceinline__ void gemm_phase(LAS unsigned char* lds, const Gemm g, const StaticOrder& S, const Epi& E) {
;     ...
;             PG8_WAIT_V(8); PG8_WAIT_L(0); PG8_BAR; PG8_MMA(1, 0, At, B0); PG8_MMA(1, 1, At, B1); PG8_BAR; PG8_SCHED;
;             PG8_LDB(B0, 1, 0); PG8_LDB(B1, 1, 1); PG8_SCHED; PG8_LDA(At, 1, 0); PG8_STAGE(PG8_SA(0, 1), a2 + hsA, voffA);
;             PG8_WAIT_V(8); PG8_WAIT_L(0); PG8_BAR; PG8_MMA(0, 0, At, B0); PG8_MMA(0, 1, At, B1); PG8_BAR; PG8_SCHED;
	s_setprio 1
	s_waitcnt lgkmcnt(0)
	v_mfma_f32_16x16x32_bf16 v[60:63], v[146:149], v[190:193], 0
	v_mfma_f32_16x16x32_bf16 v[56:59], v[166:169], v[190:193], 0
	v_mfma_f32_16x16x32_bf16 v[44:47], v[146:149], v[198:201], 0
	v_mfma_f32_16x16x32_bf16 v[40:43], v[166:169], v[198:201], 0
	v_mfma_f32_16x16x32_bf16 v[28:31], v[146:149], v[206:209], 0
	v_mfma_f32_16x16x32_bf16 v[24:27], v[166:169], v[206:209], 0
	v_mfma_f32_16x16x32_bf16 v[12:15], v[146:149], v[214:217], 0
	v_mfma_f32_16x16x32_bf16 v[8:11], v[166:169], v[214:217], 0
	v_mfma_f32_16x16x32_bf16 v[60:63], v[158:161], v[194:197], v[60:63]
	v_mfma_f32_16x16x32_bf16 v[56:59], v[170:173], v[194:197], v[56:59]
	v_mfma_f32_16x16x32_bf16 v[44:47], v[158:161], v[202:205], v[44:47]
	v_mfma_f32_16x16x32_bf16 v[40:43], v[170:173], v[202:205], v[40:43]
	v_mfma_f32_16x16x32_bf16 v[28:31], v[158:161], v[210:213], v[28:31]
	v_mfma_f32_16x16x32_bf16 v[24:27], v[170:173], v[210:213], v[24:27]
	v_mfma_f32_16x16x32_bf16 v[12:15], v[158:161], v[218:221], v[12:15]
	v_mfma_f32_16x16x32_bf16 v[8:11], v[170:173], v[218:221], v[8:11]
	s_setprio 0
	s_setprio 1
	v_mfma_f32_16x16x32_bf16 v[52:55], v[174:177], v[190:193], 0
	v_mfma_f32_16x16x32_bf16 v[48:51], v[182:185], v[190:193], 0
	v_mfma_f32_16x16x32_bf16 v[36:39], v[174:177], v[198:201], 0
	v_mfma_f32_16x16x32_bf16 v[32:35], v[182:185], v[198:201], 0
	v_mfma_f32_16x16x32_bf16 v[20:23], v[174:177], v[206:209], 0
	v_mfma_f32_16x16x32_bf16 v[16:19], v[182:185], v[206:209], 0
	v_mfma_f32_16x16x32_bf16 v[4:7], v[174:177], v[214:217], 0
	v_mfma_f32_16x16x32_bf16 v[0:3], v[182:185], v[214:217], 0
	v_mfma_f32_16x16x32_bf16 v[52:55], v[178:181], v[194:197], v[52:55]
	v_mfma_f32_16x16x32_bf16 v[48:51], v[186:189], v[194:197], v[48:51]
	v_mfma_f32_16x16x32_bf16 v[36:39], v[178:181], v[202:205], v[36:39]
	v_mfma_f32_16x16x32_bf16 v[32:35], v[186:189], v[202:205], v[32:35]
	v_mfma_f32_16x16x32_bf16 v[20:23], v[178:181], v[210:213], v[20:23]
	v_mfma_f32_16x16x32_bf16 v[16:19], v[186:189], v[210:213], v[16:19]
	v_mfma_f32_16x16x32_bf16 v[4:7], v[178:181], v[218:221], v[4:7]
	v_mfma_f32_16x16x32_bf16 v[0:3], v[186:189], v[218:221], v[0:3]
	s_setprio 0
	s_barrier
	s_add_i32 s33, 0, 0x18000
	v_add_u32_e32 v165, s33, v150
	s_add_i32 s86, 0, 0x1c000
	ds_read_b128 v[146:149], v165
	ds_read_b128 v[158:161], v165 offset:1024
	ds_read_b128 v[166:169], v165 offset:2048
	ds_read_b128 v[170:173], v165 offset:3072
	v_add_u32_e32 v165, s86, v150
	ds_read_b128 v[174:177], v165
	ds_read_b128 v[178:181], v165 offset:1024
	ds_read_b128 v[182:185], v165 offset:2048
	ds_read_b128 v[186:189], v165 offset:3072
	s_add_u32 s28, s28, 0x40000
	s_addc_u32 s29, s29, 0
	s_mov_b32 m0, s61
	v_lshl_add_u64 v[230:231], s[28:29], 0, v[136:137]
	ds_read_b128 v[190:193], v154 offset:32768
	ds_read_b128 v[194:197], v154 offset:33792
	ds_read_b128 v[198:201], v154 offset:34816
	ds_read_b128 v[202:205], v154 offset:35840
	ds_read_b128 v[206:209], v154 offset:36864
	ds_read_b128 v[210:213], v154 offset:37888
	ds_read_b128 v[214:217], v154 offset:38912
	ds_read_b128 v[218:221], v154 offset:39936
	global_load_lds_dwordx4 v[230:231], off
	v_lshl_add_u64 v[230:231], s[28:29], 0, v[132:133]
	s_mov_b32 m0, s62
	s_nop 0
	global_load_lds_dwordx4 v[230:231], off
	s_waitcnt vmcnt(8)
	s_waitcnt lgkmcnt(0)
	s_barrier
	s_setprio 1
	s_waitcnt lgkmcnt(0)
	v_mfma_f32_16x16x32_bf16 v[124:127], v[146:149], v[190:193], v[124:127]
	v_mfma_f32_16x16x32_bf16 v[120:123], v[166:169], v[190:193], v[120:123]
	v_mfma_f32_16x16x32_bf16 v[108:111], v[146:149], v[198:201], v[108:111]
	v_mfma_f32_16x16x32_bf16 v[104:107], v[166:169], v[198:201], v[104:107]
	v_mfma_f32_16x16x32_bf16 v[92:95], v[146:149], v[206:209], v[92:95]
	v_mfma_f32_16x16x32_bf16 v[88:91], v[166:169], v[206:209], v[88:91]
	v_mfma_f32_16x16x32_bf16 v[76:79], v[146:149], v[214:217], v[76:79]
	v_mfma_f32_16x16x32_bf16 v[72:75], v[166:169], v[214:217], v[72:75]
	v_mfma_f32_16x16x32_bf16 v[124:127], v[158:161], v[194:197], v[124:127]
	v_mfma_f32_16x16x32_bf16 v[120:123], v[170:173], v[194:197], v[120:123]
	v_mfma_f32_16x16x32_bf16 v[108:111], v[158:161], v[202:205], v[108:111]
	v_mfma_f32_16x16x32_bf16 v[104:107], v[170:173], v[202:205], v[104:107]
	v_mfma_f32_16x16x32_bf16 v[92:95], v[158:161], v[210:213], v[92:95]
	v_mfma_f32_16x16x32_bf16 v[88:91], v[170:173], v[210:213], v[88:91]
	v_mfma_f32_16x16x32_bf16 v[76:79], v[158:161], v[218:221], v[76:79]
	v_mfma_f32_16x16x32_bf16 v[72:75], v[170:173], v[218:221], v[72:75]
	s_setprio 0
	s_setprio 1
	v_mfma_f32_16x16x32_bf16 v[116:119], v[174:177], v[190:193], v[116:119]
	v_mfma_f32_16x16x32_bf16 v[112:115], v[182:185], v[190:193], v[112:115]
	v_mfma_f32_16x16x32_bf16 v[100:103], v[174:177], v[198:201], v[100:103]
	v_mfma_f32_16x16x32_bf16 v[96:99], v[182:185], v[198:201], v[96:99]
	v_mfma_f32_16x16x32_bf16 v[84:87], v[174:177], v[206:209], v[84:87]
	v_mfma_f32_16x16x32_bf16 v[80:83], v[182:185], v[206:209], v[80:83]
	v_mfma_f32_16x16x32_bf16 v[68:71], v[174:177], v[214:217], v[68:71]
	v_mfma_f32_16x16x32_bf16 v[64:67], v[182:185], v[214:217], v[64:67]
	v_mfma_f32_16x16x32_bf16 v[116:119], v[178:181], v[194:197], v[116:119]
	v_mfma_f32_16x16x32_bf16 v[112:115], v[186:189], v[194:197], v[112:115]
	v_mfma_f32_16x16x32_bf16 v[100:103], v[178:181], v[202:205], v[100:103]
	v_mfma_f32_16x16x32_bf16 v[96:99], v[186:189], v[202:205], v[96:99]
	v_mfma_f32_16x16x32_bf16 v[84:87], v[178:181], v[210:213], v[84:87]
	v_mfma_f32_16x16x32_bf16 v[80:83], v[186:189], v[210:213], v[80:83]
	v_mfma_f32_16x16x32_bf16 v[68:71], v[178:181], v[218:221], v[68:71]
	v_mfma_f32_16x16x32_bf16 v[64:67], v[186:189], v[218:221], v[64:67]
	s_setprio 0
	s_barrier
; #define PG8_STAGE(bufoff, gbase, voff) do { _Pragma("unroll") for (int _i = 0; _i < 2; ++_i) \
;         __builtin_amdgcn_global_load_lds((const unsigned*)((const char*)(gbase) + (voff)[_i]), (LAS unsigned*)(lds + (bufoff) + ldsw + _i * 8192), 16, 0, 0); } while (0)
; #define PG8_LDA(dst, b, h) do { _Pragma("unroll") for (int m = 0; m < 4; ++m) _Pragma("unroll") for (int k = 0; k < 2; ++k) dst[m][k] = *(const LAS bf16x8*)(lds + PG8_SA(b, h) + aoff + m * 2048 + k * 1024); } while (0)
; #define PG8_MMA(ai, bj, At, Bt) do { __builtin_amdgcn_s_setprio(1); _Pragma("unroll") for (int m = 0; m < 4; ++m) _Pragma("unroll") for (int n = 0; n < 2; ++n) _Pragma("unroll") for (int k = 0; k < 2; ++k) \
;         acc[ai][bj][m][n] = __builtin_amdgcn_mfma_f32_16x16x32_bf16(Bt[n][k], At[m][k], acc[ai][bj][m][n], 0, 0, 0); __builtin_amdgcn_s_setprio(0); } while (0)
; #define PG8_WAIT_V(n) asm volatile("s_waitcnt vmcnt(" #n ")" ::: "memory")
; #define PG8_WAIT_L(n) asm volatile("s_waitcnt lgkmcnt(" #n ")" ::: "memory")
; #define PG8_BAR __builtin_amdgcn_s_barrier()
; #define PG8_SCHED __builtin_amdgcn_sched_barrier(0)
; template <class Epi>
; __device__ __forceinline__ void gemm_phase(LAS unsigned char* lds, const Gemm g, const StaticOrder& S, const Epi& E) {
;     ...
;             PG8_LDA(At, 1, 1); PG8_STAGE(PG8_SB(1, 0), b3, voffB); PG8_STAGE(PG8_SB(1, 1), b3 + hsB, voffB); PG8_STAGE(PG8_SA(1, 0), a3, voffA);
;             PG8_WAIT_V(8); PG8_WAIT_L(0); PG8_BAR; PG8_MMA(1, 0, At, B0); PG8_MMA(1, 1, At, B1); PG8_BAR; PG8_SCHED;
;         }
	s_add_i32 s28, s33, s56
	v_lshl_add_u64 v[222:223], v[222:223], 0, s[8:9]
	s_mov_b32 m0, s28
	ds_read_b128 v[190:193], v154 offset:49152
	ds_read_b128 v[194:197], v154 offset:50176
	ds_read_b128 v[198:201], v154 offset:51200
	ds_read_b128 v[202:205], v154 offset:52224
	ds_read_b128 v[206:209], v154 offset:53248
	ds_read_b128 v[210:213], v154 offset:54272
	ds_read_b128 v[214:217], v154 offset:55296
	ds_read_b128 v[218:221], v154 offset:56320
	global_load_lds_dwordx4 v[222:223], off
	s_add_i32 m0, s28, 0x2000
	s_add_u32 s24, s24, 0x40080
	v_lshl_add_u64 v[222:223], v[224:225], 0, s[8:9]
	s_addc_u32 s25, s25, 0
	s_add_i32 s28, s86, s56
	global_load_lds_dwordx4 v[222:223], off
	v_lshl_add_u64 v[222:223], s[24:25], 0, v[134:135]
	s_mov_b32 m0, s28
	s_nop 0
	global_load_lds_dwordx4 v[222:223], off
	v_lshl_add_u64 v[222:223], s[24:25], 0, v[130:131]
	s_add_i32 m0, s28, 0x2000
	s_nop 0
	global_load_lds_dwordx4 v[222:223], off
	v_lshl_add_u64 v[222:223], v[226:227], 0, s[8:9]
	s_mov_b32 m0, s64
	s_nop 0
	global_load_lds_dwordx4 v[222:223], off
	v_lshl_add_u64 v[222:223], v[228:229], 0, s[8:9]
	s_mov_b32 m0, s65
	s_nop 0
	global_load_lds_dwordx4 v[222:223], off
	s_waitcnt vmcnt(8)
	s_waitcnt lgkmcnt(0)
	s_barrier
	s_setprio 1
	s_waitcnt lgkmcnt(0)
	v_mfma_f32_16x16x32_bf16 v[60:63], v[146:149], v[190:193], v[60:63]
	v_mfma_f32_16x16x32_bf16 v[56:59], v[166:169], v[190:193], v[56:59]
	v_mfma_f32_16x16x32_bf16 v[44:47], v[146:149], v[198:201], v[44:47]
	v_mfma_f32_16x16x32_bf16 v[40:43], v[166:169], v[198:201], v[40:43]
	v_mfma_f32_16x16x32_bf16 v[28:31], v[146:149], v[206:209], v[28:31]
	v_mfma_f32_16x16x32_bf16 v[24:27], v[166:169], v[206:209], v[24:27]
	v_mfma_f32_16x16x32_bf16 v[12:15], v[146:149], v[214:217], v[12:15]
	v_mfma_f32_16x16x32_bf16 v[8:11], v[166:169], v[214:217], v[8:11]
	v_mfma_f32_16x16x32_bf16 v[60:63], v[158:161], v[194:197], v[60:63]
	v_mfma_f32_16x16x32_bf16 v[56:59], v[170:173], v[194:197], v[56:59]
	v_mfma_f32_16x16x32_bf16 v[44:47], v[158:161], v[202:205], v[44:47]
	v_mfma_f32_16x16x32_bf16 v[40:43], v[170:173], v[202:205], v[40:43]
	v_mfma_f32_16x16x32_bf16 v[28:31], v[158:161], v[210:213], v[28:31]
	v_mfma_f32_16x16x32_bf16 v[24:27], v[170:173], v[210:213], v[24:27]
	v_mfma_f32_16x16x32_bf16 v[12:15], v[158:161], v[218:221], v[12:15]
	v_mfma_f32_16x16x32_bf16 v[8:11], v[170:173], v[218:221], v[8:11]
	s_setprio 0
	s_setprio 1
	v_mfma_f32_16x16x32_bf16 v[52:55], v[174:177], v[190:193], v[52:55]
	v_mfma_f32_16x16x32_bf16 v[48:51], v[182:185], v[190:193], v[48:51]
	v_mfma_f32_16x16x32_bf16 v[36:39], v[174:177], v[198:201], v[36:39]
	v_mfma_f32_16x16x32_bf16 v[32:35], v[182:185], v[198:201], v[32:35]
	v_mfma_f32_16x16x32_bf16 v[20:23], v[174:177], v[206:209], v[20:23]
	v_mfma_f32_16x16x32_bf16 v[16:19], v[182:185], v[206:209], v[16:19]
	v_mfma_f32_16x16x32_bf16 v[4:7], v[174:177], v[214:217], v[4:7]
	v_mfma_f32_16x16x32_bf16 v[0:3], v[182:185], v[214:217], v[0:3]
	v_mfma_f32_16x16x32_bf16 v[52:55], v[178:181], v[194:197], v[52:55]
	v_mfma_f32_16x16x32_bf16 v[48:51], v[186:189], v[194:197], v[48:51]
	v_mfma_f32_16x16x32_bf16 v[36:39], v[178:181], v[202:205], v[36:39]
	v_mfma_f32_16x16x32_bf16 v[32:35], v[186:189], v[202:205], v[32:35]
	v_mfma_f32_16x16x32_bf16 v[20:23], v[178:181], v[210:213], v[20:23]
	v_mfma_f32_16x16x32_bf16 v[16:19], v[186:189], v[210:213], v[16:19]
	v_mfma_f32_16x16x32_bf16 v[4:7], v[178:181], v[218:221], v[4:7]
	v_mfma_f32_16x16x32_bf16 v[0:3], v[186:189], v[218:221], v[0:3]
	s_setprio 0
	s_barrier
	s_add_i32 s85, s85, 2
	s_add_u32 s22, s22, 0x100
	s_addc_u32 s23, s23, 0
	s_add_u32 s83, s83, 0x100
	s_addc_u32 s84, s84, 0
	s_cmp_gt_u32 s85, 13
	s_cbranch_scc0 .LBB0_223
	s_branch .Lpeel_exit0

; __device__ __forceinline__ float sigmoidf_(float x) { return __builtin_amdgcn_rcpf(1.f + __expf(-x)); }
;     __device__ __forceinline__ void operator()(const AccT& acc, const Unit& u, int wr, int wc, int fr, int fq) const {
;         const int row0 = u.pm * BM + wr * 64 + fr, col = u.pn * 128 + wc * 32 + 8 * fq;
; #pragma unroll
;         for (int ai = 0; ai < 2; ++ai)
; #pragma unroll
;             for (int m = 0; m < 4; ++m) {
;                 const int row = row0 + ai * HALF + m * 16;
;                 const float rs = rsqrtf(ss[row] * (1.f / 1024.f) + EPS);
;                 float o[8];
; #pragma unroll
;                 for (int n = 0; n < 2; ++n)
; #pragma unroll
;                     for (int j = 0; j < 4; ++j) { const float gt = acc[ai][0][m][n][j] * rs, up = acc[ai][1][m][n][j] * rs; o[n * 4 + j] = gt * up * sigmoidf_(gt); }
;                 *(u32x4*)(O + (size_t)row * FF + col) = pack8(o);
.LBB0_226:
	v_lshl_add_u32 v146, s4, 8, v129
	v_ashrrev_i32_e32 v147, 31, v146
	v_lshl_add_u64 v[148:149], v[146:147], 2, s[70:71]
	v_mov_b32_e32 v166, v122
	v_mov_b32_e32 v167, v114
	v_mov_b32_e32 v114, v123
	v_lshl_or_b32 v158, s5, 7, v151
	v_mov_b32_e32 v160, v124
	v_mov_b32_e32 v161, v116
	v_mov_b32_e32 v116, v125
	v_mov_b32_e32 v124, v126
	v_mov_b32_e32 v125, v118
	v_mov_b32_e32 v118, v127
	v_mov_b32_e32 v126, v120
	v_mov_b32_e32 v127, v112
	v_mov_b32_e32 v112, v121
	v_mov_b64_e32 v[120:121], s[44:45]
	v_ashrrev_i32_e32 v159, 31, v158
	v_mad_i64_i32 v[168:169], s[4:5], v146, s79, v[120:121]
	s_nop 0
	v_fmamk_f32 v122, v232, 0x3a800000, v155
	v_mul_f32_e32 v123, 0x4b800000, v122
	v_cmp_gt_f32_e32 vcc, s78, v122
	s_nop 1
	v_cndmask_b32_e32 v122, v122, v123, vcc
	v_rsq_f32_e32 v147, v122
	v_lshlrev_b64 v[122:123], 1, v[158:159]
	v_lshl_add_u64 v[158:159], v[168:169], 0, v[122:123]
	v_mul_f32_e32 v165, 0x45800000, v147
	v_cndmask_b32_e32 v168, v147, v165, vcc
	v_pk_mul_f32 v[114:115], v[114:115], v[168:169] op_sel_hi:[1,0]
	v_pk_mul_f32 v[160:161], v[160:161], v[168:169] op_sel_hi:[1,0]
	v_pk_mul_f32 v[116:117], v[116:117], v[168:169] op_sel_hi:[1,0]
	v_pk_mul_f32 v[124:125], v[124:125], v[168:169] op_sel_hi:[1,0]
	v_pk_mul_f32 v[118:119], v[118:119], v[168:169] op_sel_hi:[1,0]
	v_pk_mul_f32 v[126:127], v[126:127], v[168:169] op_sel_hi:[1,0]
	v_pk_mul_f32 v[112:113], v[112:113], v[168:169] op_sel_hi:[1,0]
	v_pk_mul_f32 v[166:167], v[166:167], v[168:169] op_sel_hi:[1,0]
	v_mul_f32_e32 v115, v114, v115
	v_mul_f32_e32 v114, 0xbfb8aa3b, v114
	v_mul_f32_e32 v147, v160, v161
	v_mul_f32_e32 v160, 0xbfb8aa3b, v160
	v_mul_f32_e32 v117, v116, v117
	v_mul_f32_e32 v116, 0xbfb8aa3b, v116
	v_mul_f32_e32 v125, v124, v125
	v_mul_f32_e32 v124, 0xbfb8aa3b, v124
	v_mul_f32_e32 v119, v118, v119
	v_mul_f32_e32 v118, 0xbfb8aa3b, v118
	v_mul_f32_e32 v127, v126, v127
	v_mul_f32_e32 v126, 0xbfb8aa3b, v126
	v_mul_f32_e32 v113, v112, v113
	v_mul_f32_e32 v112, 0xbfb8aa3b, v112
	v_mul_f32_e32 v165, 0xbfb8aa3b, v166
	v_exp_f32_e32 v114, v114
	v_exp_f32_e32 v160, v160
	v_exp_f32_e32 v116, v116
	v_exp_f32_e32 v124, v124
	v_exp_f32_e32 v118, v118
	v_exp_f32_e32 v126, v126
	v_exp_f32_e32 v112, v112
	v_exp_f32_e32 v165, v165
	v_add_f32_e32 v114, 1.0, v114
	v_add_f32_e32 v160, 1.0, v160
	v_add_f32_e32 v116, 1.0, v116
	v_add_f32_e32 v124, 1.0, v124
	v_add_f32_e32 v118, 1.0, v118
	v_add_f32_e32 v126, 1.0, v126
	v_add_f32_e32 v112, 1.0, v112
	v_add_f32_e32 v165, 1.0, v165
	v_rcp_f32_e32 v114, v114
	v_rcp_f32_e32 v160, v160
	v_rcp_f32_e32 v116, v116
	v_rcp_f32_e32 v124, v124
	v_rcp_f32_e32 v118, v118
	v_rcp_f32_e32 v126, v126
	v_rcp_f32_e32 v112, v112
	v_rcp_f32_e32 v165, v165
	v_mul_f32_e32 v161, v166, v167
	v_mul_f32_e32 v115, v115, v114
	v_mul_f32_e32 v147, v147, v160
	v_mul_f32_e32 v116, v117, v116
	v_mul_f32_e32 v117, v125, v124
	v_mul_f32_e32 v118, v119, v118
	v_mul_f32_e32 v119, v127, v126
	v_mul_f32_e32 v124, v113, v112
	v_mul_f32_e32 v125, v161, v165
	v_cvt_pk_bf16_f32 v112, v147, v116
	v_cvt_pk_bf16_f32 v113, v117, v118
	v_cvt_pk_bf16_f32 v114, v119, v124
	v_cvt_pk_bf16_f32 v115, v125, v115
	global_store_dwordx4 v[158:159], v[112:115], off
	s_nop 0
	s_nop 0
	v_mov_b32_e32 v113, v100
	v_mov_b32_e32 v100, v109
	v_mov_b32_e32 v109, v102
	v_mov_b32_e32 v102, v111
	v_mov_b32_e32 v111, v96
	v_mov_b32_e32 v96, v105
	v_mov_b32_e32 v105, v98
	v_mov_b32_e32 v98, v107
	v_mov_b32_e32 v112, v108
	v_mov_b32_e32 v108, v110
	v_mov_b32_e32 v110, v104
	v_mov_b32_e32 v104, v106
	v_or_b32_e32 v106, 16, v146
	s_nop 0
	v_fmamk_f32 v107, v233, 0x3a800000, v155
	v_mul_f32_e32 v114, 0x4b800000, v107
	v_cmp_gt_f32_e32 vcc, s78, v107
	s_nop 1
	v_cndmask_b32_e32 v107, v107, v114, vcc
	v_rsq_f32_e32 v114, v107
	v_mad_i64_i32 v[106:107], s[4:5], v106, s79, v[120:121]
	v_lshl_add_u64 v[106:107], v[106:107], 0, v[122:123]
	v_mul_f32_e32 v115, 0x45800000, v114
	v_cndmask_b32_e32 v114, v114, v115, vcc
	v_pk_mul_f32 v[98:99], v[98:99], v[114:115] op_sel_hi:[1,0]
	v_pk_mul_f32 v[112:113], v[112:113], v[114:115] op_sel_hi:[1,0]
	v_pk_mul_f32 v[100:101], v[100:101], v[114:115] op_sel_hi:[1,0]
	v_pk_mul_f32 v[108:109], v[108:109], v[114:115] op_sel_hi:[1,0]
	v_pk_mul_f32 v[102:103], v[102:103], v[114:115] op_sel_hi:[1,0]
	v_pk_mul_f32 v[110:111], v[110:111], v[114:115] op_sel_hi:[1,0]
	v_pk_mul_f32 v[96:97], v[96:97], v[114:115] op_sel_hi:[1,0]
	v_pk_mul_f32 v[104:105], v[104:105], v[114:115] op_sel_hi:[1,0]
	v_mul_f32_e32 v99, v98, v99
	v_mul_f32_e32 v98, 0xbfb8aa3b, v98
	v_mul_f32_e32 v113, v112, v113
	v_mul_f32_e32 v112, 0xbfb8aa3b, v112
	v_mul_f32_e32 v101, v100, v101
	v_mul_f32_e32 v100, 0xbfb8aa3b, v100
	v_mul_f32_e32 v109, v108, v109
	v_mul_f32_e32 v108, 0xbfb8aa3b, v108
	v_mul_f32_e32 v103, v102, v103
	v_mul_f32_e32 v102, 0xbfb8aa3b, v102
	v_mul_f32_e32 v111, v110, v111
	v_mul_f32_e32 v110, 0xbfb8aa3b, v110
	v_mul_f32_e32 v97, v96, v97
	v_mul_f32_e32 v96, 0xbfb8aa3b, v96
	v_mul_f32_e32 v105, v104, v105
	v_mul_f32_e32 v104, 0xbfb8aa3b, v104
	v_exp_f32_e32 v98, v98
	v_exp_f32_e32 v112, v112
	v_exp_f32_e32 v100, v100
	v_exp_f32_e32 v108, v108
	v_exp_f32_e32 v102, v102
	v_exp_f32_e32 v110, v110
	v_exp_f32_e32 v96, v96
	v_exp_f32_e32 v104, v104
	v_add_f32_e32 v98, 1.0, v98
	v_add_f32_e32 v112, 1.0, v112
	v_add_f32_e32 v100, 1.0, v100
	v_add_f32_e32 v108, 1.0, v108
	v_add_f32_e32 v102, 1.0, v102
	v_add_f32_e32 v110, 1.0, v110
	v_add_f32_e32 v96, 1.0, v96
	v_add_f32_e32 v104, 1.0, v104
	v_rcp_f32_e32 v98, v98
	v_rcp_f32_e32 v112, v112
	v_rcp_f32_e32 v100, v100
	v_rcp_f32_e32 v108, v108
	v_rcp_f32_e32 v102, v102
	v_rcp_f32_e32 v110, v110
	v_rcp_f32_e32 v96, v96
	v_rcp_f32_e32 v104, v104
; __device__ __forceinline__ float sigmoidf_(float x) { return __builtin_amdgcn_rcpf(1.f + __expf(-x)); }
;     __device__ __forceinline__ void operator()(const AccT& acc, const Unit& u, int wr, int wc, int fr, int fq) const {
;         const int row0 = u.pm * BM + wr * 64 + fr, col = u.pn * 128 + wc * 32 + 8 * fq;
; #pragma unroll
;         for (int ai = 0; ai < 2; ++ai)
; #pragma unroll
;             for (int m = 0; m < 4; ++m) {
;                 const int row = row0 + ai * HALF + m * 16;
;                 const float rs = rsqrtf(ss[row] * (1.f / 1024.f) + EPS);
;                 float o[8];
; #pragma unroll
;                 for (int n = 0; n < 2; ++n)
; #pragma unroll
;                     for (int j = 0; j < 4; ++j) { const float gt = acc[ai][0][m][n][j] * rs, up = acc[ai][1][m][n][j] * rs; o[n * 4 + j] = gt * up * sigmoidf_(gt); }
;                 *(u32x4*)(O + (size_t)row * FF + col) = pack8(o);
	v_mul_f32_e32 v99, v99, v98
	v_mul_f32_e32 v112, v113, v112
	v_mul_f32_e32 v100, v101, v100
	v_mul_f32_e32 v101, v109, v108
	v_mul_f32_e32 v102, v103, v102
	v_mul_f32_e32 v103, v111, v110
	v_mul_f32_e32 v108, v97, v96
	v_mul_f32_e32 v104, v105, v104
	v_cvt_pk_bf16_f32 v96, v112, v100
	v_cvt_pk_bf16_f32 v97, v101, v102
	v_cvt_pk_bf16_f32 v98, v103, v108
	v_cvt_pk_bf16_f32 v99, v104, v99
	global_store_dwordx4 v[106:107], v[96:99], off
	s_nop 0
	s_nop 0
	v_mov_b32_e32 v97, v84
	v_mov_b32_e32 v84, v93
	v_mov_b32_e32 v93, v86
	v_mov_b32_e32 v86, v95
	v_mov_b32_e32 v95, v80
	v_mov_b32_e32 v80, v89
	v_mov_b32_e32 v89, v82
	v_mov_b32_e32 v82, v91
	v_mov_b32_e32 v96, v92
	v_mov_b32_e32 v92, v94
	v_mov_b32_e32 v94, v88
	v_mov_b32_e32 v88, v90
	v_or_b32_e32 v90, 32, v146
	s_nop 0
	v_fmamk_f32 v91, v234, 0x3a800000, v155
	v_mul_f32_e32 v98, 0x4b800000, v91
	v_cmp_gt_f32_e32 vcc, s78, v91
	s_nop 1
	v_cndmask_b32_e32 v91, v91, v98, vcc
	v_rsq_f32_e32 v98, v91
	v_mad_i64_i32 v[90:91], s[4:5], v90, s79, v[120:121]
	v_lshl_add_u64 v[90:91], v[90:91], 0, v[122:123]
	v_mul_f32_e32 v99, 0x45800000, v98
	v_cndmask_b32_e32 v98, v98, v99, vcc
	v_pk_mul_f32 v[82:83], v[82:83], v[98:99] op_sel_hi:[1,0]
	v_pk_mul_f32 v[96:97], v[96:97], v[98:99] op_sel_hi:[1,0]
	v_pk_mul_f32 v[84:85], v[84:85], v[98:99] op_sel_hi:[1,0]
	v_pk_mul_f32 v[92:93], v[92:93], v[98:99] op_sel_hi:[1,0]
	v_pk_mul_f32 v[86:87], v[86:87], v[98:99] op_sel_hi:[1,0]
	v_pk_mul_f32 v[94:95], v[94:95], v[98:99] op_sel_hi:[1,0]
	v_pk_mul_f32 v[80:81], v[80:81], v[98:99] op_sel_hi:[1,0]
	v_pk_mul_f32 v[88:89], v[88:89], v[98:99] op_sel_hi:[1,0]
	v_mul_f32_e32 v83, v82, v83
	v_mul_f32_e32 v82, 0xbfb8aa3b, v82
	v_mul_f32_e32 v97, v96, v97
	v_mul_f32_e32 v96, 0xbfb8aa3b, v96
	v_mul_f32_e32 v85, v84, v85
	v_mul_f32_e32 v84, 0xbfb8aa3b, v84
	v_mul_f32_e32 v93, v92, v93
	v_mul_f32_e32 v92, 0xbfb8aa3b, v92
	v_mul_f32_e32 v87, v86, v87
	v_mul_f32_e32 v86, 0xbfb8aa3b, v86
	v_mul_f32_e32 v95, v94, v95
	v_mul_f32_e32 v94, 0xbfb8aa3b, v94
	v_mul_f32_e32 v81, v80, v81
	v_mul_f32_e32 v80, 0xbfb8aa3b, v80
	v_mul_f32_e32 v89, v88, v89
	v_mul_f32_e32 v88, 0xbfb8aa3b, v88
	v_exp_f32_e32 v82, v82
	v_exp_f32_e32 v96, v96
	v_exp_f32_e32 v84, v84
	v_exp_f32_e32 v92, v92
	v_exp_f32_e32 v86, v86
	v_exp_f32_e32 v94, v94
	v_exp_f32_e32 v80, v80
	v_exp_f32_e32 v88, v88
	v_add_f32_e32 v82, 1.0, v82
	v_add_f32_e32 v96, 1.0, v96
	v_add_f32_e32 v84, 1.0, v84
	v_add_f32_e32 v92, 1.0, v92
	v_add_f32_e32 v86, 1.0, v86
	v_add_f32_e32 v94, 1.0, v94
	v_add_f32_e32 v80, 1.0, v80
	v_add_f32_e32 v88, 1.0, v88
	v_rcp_f32_e32 v82, v82
	v_rcp_f32_e32 v96, v96
	v_rcp_f32_e32 v84, v84
	v_rcp_f32_e32 v92, v92
	v_rcp_f32_e32 v86, v86
	v_rcp_f32_e32 v94, v94
	v_rcp_f32_e32 v80, v80
	v_rcp_f32_e32 v88, v88
	v_mul_f32_e32 v83, v83, v82
	v_mul_f32_e32 v96, v97, v96
	v_mul_f32_e32 v84, v85, v84
	v_mul_f32_e32 v85, v93, v92
	v_mul_f32_e32 v86, v87, v86
	v_mul_f32_e32 v87, v95, v94
	v_mul_f32_e32 v92, v81, v80
	v_mul_f32_e32 v88, v89, v88
	v_cvt_pk_bf16_f32 v80, v96, v84
	v_cvt_pk_bf16_f32 v81, v85, v86
	v_cvt_pk_bf16_f32 v82, v87, v92
	v_cvt_pk_bf16_f32 v83, v88, v83
	global_store_dwordx4 v[90:91], v[80:83], off
	s_nop 0
	s_nop 0
	v_mov_b32_e32 v81, v68
	v_mov_b32_e32 v68, v77
	v_mov_b32_e32 v77, v70
	v_mov_b32_e32 v70, v79
	v_mov_b32_e32 v79, v64
	v_mov_b32_e32 v64, v73
	v_mov_b32_e32 v73, v66
	v_mov_b32_e32 v66, v75
	v_mov_b32_e32 v80, v76
	v_mov_b32_e32 v76, v78
	v_mov_b32_e32 v78, v72
	v_mov_b32_e32 v72, v74
	v_or_b32_e32 v74, 48, v146
	s_nop 0
	v_fmamk_f32 v75, v235, 0x3a800000, v155
	v_mul_f32_e32 v82, 0x4b800000, v75
	v_cmp_gt_f32_e32 vcc, s78, v75
	s_nop 1
	v_cndmask_b32_e32 v75, v75, v82, vcc
	v_rsq_f32_e32 v82, v75
	v_mad_i64_i32 v[74:75], s[4:5], v74, s79, v[120:121]
	v_lshl_add_u64 v[74:75], v[74:75], 0, v[122:123]
	v_mul_f32_e32 v83, 0x45800000, v82
	v_cndmask_b32_e32 v82, v82, v83, vcc
	v_pk_mul_f32 v[66:67], v[66:67], v[82:83] op_sel_hi:[1,0]
	v_pk_mul_f32 v[80:81], v[80:81], v[82:83] op_sel_hi:[1,0]
	v_pk_mul_f32 v[68:69], v[68:69], v[82:83] op_sel_hi:[1,0]
	v_pk_mul_f32 v[76:77], v[76:77], v[82:83] op_sel_hi:[1,0]
	v_pk_mul_f32 v[70:71], v[70:71], v[82:83] op_sel_hi:[1,0]
	v_pk_mul_f32 v[78:79], v[78:79], v[82:83] op_sel_hi:[1,0]
	v_pk_mul_f32 v[64:65], v[64:65], v[82:83] op_sel_hi:[1,0]
	v_pk_mul_f32 v[72:73], v[72:73], v[82:83] op_sel_hi:[1,0]
	v_mul_f32_e32 v67, v66, v67
	v_mul_f32_e32 v66, 0xbfb8aa3b, v66
	v_mul_f32_e32 v81, v80, v81
	v_mul_f32_e32 v80, 0xbfb8aa3b, v80
	v_mul_f32_e32 v69, v68, v69
	v_mul_f32_e32 v68, 0xbfb8aa3b, v68
	v_mul_f32_e32 v77, v76, v77
	v_mul_f32_e32 v76, 0xbfb8aa3b, v76
	v_mul_f32_e32 v71, v70, v71
	v_mul_f32_e32 v70, 0xbfb8aa3b, v70
	v_mul_f32_e32 v79, v78, v79
	v_mul_f32_e32 v78, 0xbfb8aa3b, v78
	v_mul_f32_e32 v65, v64, v65
	v_mul_f32_e32 v64, 0xbfb8aa3b, v64
	v_mul_f32_e32 v73, v72, v73
	v_mul_f32_e32 v72, 0xbfb8aa3b, v72
	v_exp_f32_e32 v66, v66
	v_exp_f32_e32 v80, v80
	v_exp_f32_e32 v68, v68
	v_exp_f32_e32 v76, v76
	v_exp_f32_e32 v70, v70
	v_exp_f32_e32 v78, v78
	v_exp_f32_e32 v64, v64
	v_exp_f32_e32 v72, v72
	v_add_f32_e32 v66, 1.0, v66
	v_add_f32_e32 v80, 1.0, v80
	v_add_f32_e32 v68, 1.0, v68
	v_add_f32_e32 v76, 1.0, v76
	v_add_f32_e32 v70, 1.0, v70
	v_add_f32_e32 v78, 1.0, v78
	v_add_f32_e32 v64, 1.0, v64
	v_add_f32_e32 v72, 1.0, v72
	v_rcp_f32_e32 v66, v66
	v_rcp_f32_e32 v80, v80
	v_rcp_f32_e32 v68, v68
	v_rcp_f32_e32 v76, v76
	v_rcp_f32_e32 v70, v70
	v_rcp_f32_e32 v78, v78
	v_rcp_f32_e32 v64, v64
	v_rcp_f32_e32 v72, v72
	v_mul_f32_e32 v67, v67, v66
	v_mul_f32_e32 v80, v81, v80
	v_mul_f32_e32 v68, v69, v68
	v_mul_f32_e32 v69, v77, v76
	v_mul_f32_e32 v70, v71, v70
	v_mul_f32_e32 v71, v79, v78
; __device__ __forceinline__ float sigmoidf_(float x) { return __builtin_amdgcn_rcpf(1.f + __expf(-x)); }
;     __device__ __forceinline__ void operator()(const AccT& acc, const Unit& u, int wr, int wc, int fr, int fq) const {
;         const int row0 = u.pm * BM + wr * 64 + fr, col = u.pn * 128 + wc * 32 + 8 * fq;
; #pragma unroll
;         for (int ai = 0; ai < 2; ++ai)
; #pragma unroll
;             for (int m = 0; m < 4; ++m) {
;                 const int row = row0 + ai * HALF + m * 16;
;                 const float rs = rsqrtf(ss[row] * (1.f / 1024.f) + EPS);
;                 float o[8];
; #pragma unroll
;                 for (int n = 0; n < 2; ++n)
; #pragma unroll
;                     for (int j = 0; j < 4; ++j) { const float gt = acc[ai][0][m][n][j] * rs, up = acc[ai][1][m][n][j] * rs; o[n * 4 + j] = gt * up * sigmoidf_(gt); }
;                 *(u32x4*)(O + (size_t)row * FF + col) = pack8(o);
	v_mul_f32_e32 v76, v65, v64
	v_mul_f32_e32 v72, v73, v72
	v_cvt_pk_bf16_f32 v64, v80, v68
	v_cvt_pk_bf16_f32 v65, v69, v70
	v_cvt_pk_bf16_f32 v66, v71, v76
	v_cvt_pk_bf16_f32 v67, v72, v67
	global_store_dwordx4 v[74:75], v[64:67], off
	s_nop 0
	s_nop 0
	v_mov_b32_e32 v65, v52
	v_mov_b32_e32 v52, v61
	v_mov_b32_e32 v61, v54
	v_mov_b32_e32 v54, v63
	v_mov_b32_e32 v63, v48
	v_mov_b32_e32 v48, v57
	v_mov_b32_e32 v57, v50
	v_mov_b32_e32 v50, v59
	v_mov_b32_e32 v64, v60
	v_mov_b32_e32 v60, v62
	v_mov_b32_e32 v62, v56
	v_mov_b32_e32 v56, v58
	v_add_u32_e32 v58, 0x80, v146
	s_nop 0
	v_fmamk_f32 v59, v236, 0x3a800000, v155
	v_mul_f32_e32 v66, 0x4b800000, v59
	v_cmp_gt_f32_e32 vcc, s78, v59
	s_nop 1
	v_cndmask_b32_e32 v59, v59, v66, vcc
	v_rsq_f32_e32 v66, v59
	v_mad_i64_i32 v[58:59], s[4:5], v58, s79, v[120:121]
	v_lshl_add_u64 v[58:59], v[58:59], 0, v[122:123]
	v_mul_f32_e32 v67, 0x45800000, v66
	v_cndmask_b32_e32 v66, v66, v67, vcc
	v_pk_mul_f32 v[50:51], v[50:51], v[66:67] op_sel_hi:[1,0]
	v_pk_mul_f32 v[64:65], v[64:65], v[66:67] op_sel_hi:[1,0]
	v_pk_mul_f32 v[52:53], v[52:53], v[66:67] op_sel_hi:[1,0]
	v_pk_mul_f32 v[60:61], v[60:61], v[66:67] op_sel_hi:[1,0]
	v_pk_mul_f32 v[54:55], v[54:55], v[66:67] op_sel_hi:[1,0]
	v_pk_mul_f32 v[62:63], v[62:63], v[66:67] op_sel_hi:[1,0]
	v_pk_mul_f32 v[48:49], v[48:49], v[66:67] op_sel_hi:[1,0]
	v_pk_mul_f32 v[56:57], v[56:57], v[66:67] op_sel_hi:[1,0]
	v_mul_f32_e32 v51, v50, v51
	v_mul_f32_e32 v50, 0xbfb8aa3b, v50
	v_mul_f32_e32 v65, v64, v65
	v_mul_f32_e32 v64, 0xbfb8aa3b, v64
	v_mul_f32_e32 v53, v52, v53
	v_mul_f32_e32 v52, 0xbfb8aa3b, v52
	v_mul_f32_e32 v61, v60, v61
	v_mul_f32_e32 v60, 0xbfb8aa3b, v60
	v_mul_f32_e32 v55, v54, v55
	v_mul_f32_e32 v54, 0xbfb8aa3b, v54
	v_mul_f32_e32 v63, v62, v63
	v_mul_f32_e32 v62, 0xbfb8aa3b, v62
	v_mul_f32_e32 v49, v48, v49
	v_mul_f32_e32 v48, 0xbfb8aa3b, v48
	v_mul_f32_e32 v57, v56, v57
	v_mul_f32_e32 v56, 0xbfb8aa3b, v56
	v_exp_f32_e32 v50, v50
	v_exp_f32_e32 v64, v64
	v_exp_f32_e32 v52, v52
	v_exp_f32_e32 v60, v60
	v_exp_f32_e32 v54, v54
	v_exp_f32_e32 v62, v62
	v_exp_f32_e32 v48, v48
	v_exp_f32_e32 v56, v56
	v_add_f32_e32 v50, 1.0, v50
	v_add_f32_e32 v64, 1.0, v64
	v_add_f32_e32 v52, 1.0, v52
	v_add_f32_e32 v60, 1.0, v60
	v_add_f32_e32 v54, 1.0, v54
	v_add_f32_e32 v62, 1.0, v62
	v_add_f32_e32 v48, 1.0, v48
	v_add_f32_e32 v56, 1.0, v56
	v_rcp_f32_e32 v50, v50
	v_rcp_f32_e32 v64, v64
	v_rcp_f32_e32 v52, v52
	v_rcp_f32_e32 v60, v60
	v_rcp_f32_e32 v54, v54
	v_rcp_f32_e32 v62, v62
	v_rcp_f32_e32 v48, v48
	v_rcp_f32_e32 v56, v56
	v_mul_f32_e32 v51, v51, v50
	v_mul_f32_e32 v64, v65, v64
	v_mul_f32_e32 v52, v53, v52
	v_mul_f32_e32 v53, v61, v60
	v_mul_f32_e32 v54, v55, v54
	v_mul_f32_e32 v55, v63, v62
	v_mul_f32_e32 v60, v49, v48
	v_mul_f32_e32 v56, v57, v56
	v_cvt_pk_bf16_f32 v48, v64, v52
	v_cvt_pk_bf16_f32 v49, v53, v54
	v_cvt_pk_bf16_f32 v50, v55, v60
	v_cvt_pk_bf16_f32 v51, v56, v51
	global_store_dwordx4 v[58:59], v[48:51], off
	s_nop 0
	s_nop 0
	v_mov_b32_e32 v49, v36
	v_mov_b32_e32 v36, v45
	v_mov_b32_e32 v45, v38
	v_mov_b32_e32 v38, v47
	v_mov_b32_e32 v47, v32
	v_mov_b32_e32 v32, v41
	v_mov_b32_e32 v41, v34
	v_mov_b32_e32 v34, v43
	v_mov_b32_e32 v48, v44
	v_mov_b32_e32 v44, v46
	v_mov_b32_e32 v46, v40
	v_mov_b32_e32 v40, v42
	v_add_u32_e32 v42, 0x90, v146
	s_nop 0
	v_fmamk_f32 v43, v237, 0x3a800000, v155
	v_mul_f32_e32 v50, 0x4b800000, v43
	v_cmp_gt_f32_e32 vcc, s78, v43
	s_nop 1
	v_cndmask_b32_e32 v43, v43, v50, vcc
	v_rsq_f32_e32 v50, v43
	v_mad_i64_i32 v[42:43], s[4:5], v42, s79, v[120:121]
	v_lshl_add_u64 v[42:43], v[42:43], 0, v[122:123]
	v_mul_f32_e32 v51, 0x45800000, v50
	v_cndmask_b32_e32 v50, v50, v51, vcc
	v_pk_mul_f32 v[34:35], v[34:35], v[50:51] op_sel_hi:[1,0]
	v_pk_mul_f32 v[48:49], v[48:49], v[50:51] op_sel_hi:[1,0]
	v_pk_mul_f32 v[36:37], v[36:37], v[50:51] op_sel_hi:[1,0]
	v_pk_mul_f32 v[44:45], v[44:45], v[50:51] op_sel_hi:[1,0]
	v_pk_mul_f32 v[38:39], v[38:39], v[50:51] op_sel_hi:[1,0]
	v_pk_mul_f32 v[46:47], v[46:47], v[50:51] op_sel_hi:[1,0]
	v_pk_mul_f32 v[32:33], v[32:33], v[50:51] op_sel_hi:[1,0]
	v_pk_mul_f32 v[40:41], v[40:41], v[50:51] op_sel_hi:[1,0]
	v_mul_f32_e32 v35, v34, v35
	v_mul_f32_e32 v34, 0xbfb8aa3b, v34
	v_mul_f32_e32 v49, v48, v49
	v_mul_f32_e32 v48, 0xbfb8aa3b, v48
	v_mul_f32_e32 v37, v36, v37
	v_mul_f32_e32 v36, 0xbfb8aa3b, v36
	v_mul_f32_e32 v45, v44, v45
	v_mul_f32_e32 v44, 0xbfb8aa3b, v44
	v_mul_f32_e32 v39, v38, v39
	v_mul_f32_e32 v38, 0xbfb8aa3b, v38
	v_mul_f32_e32 v47, v46, v47
	v_mul_f32_e32 v46, 0xbfb8aa3b, v46
	v_mul_f32_e32 v33, v32, v33
	v_mul_f32_e32 v32, 0xbfb8aa3b, v32
	v_mul_f32_e32 v41, v40, v41
	v_mul_f32_e32 v40, 0xbfb8aa3b, v40
	v_exp_f32_e32 v34, v34
	v_exp_f32_e32 v48, v48
	v_exp_f32_e32 v36, v36
	v_exp_f32_e32 v44, v44
	v_exp_f32_e32 v38, v38
	v_exp_f32_e32 v46, v46
	v_exp_f32_e32 v32, v32
	v_exp_f32_e32 v40, v40
	v_add_f32_e32 v34, 1.0, v34
	v_add_f32_e32 v48, 1.0, v48
	v_add_f32_e32 v36, 1.0, v36
	v_add_f32_e32 v44, 1.0, v44
	v_add_f32_e32 v38, 1.0, v38
	v_add_f32_e32 v46, 1.0, v46
	v_add_f32_e32 v32, 1.0, v32
	v_add_f32_e32 v40, 1.0, v40
	v_rcp_f32_e32 v34, v34
	v_rcp_f32_e32 v48, v48
	v_rcp_f32_e32 v36, v36
	v_rcp_f32_e32 v44, v44
	v_rcp_f32_e32 v38, v38
	v_rcp_f32_e32 v46, v46
	v_rcp_f32_e32 v32, v32
	v_rcp_f32_e32 v40, v40
	v_mul_f32_e32 v35, v35, v34
	v_mul_f32_e32 v48, v49, v48
	v_mul_f32_e32 v36, v37, v36
	v_mul_f32_e32 v37, v45, v44
	v_mul_f32_e32 v38, v39, v38
	v_mul_f32_e32 v39, v47, v46
	v_mul_f32_e32 v44, v33, v32
	v_mul_f32_e32 v40, v41, v40
	v_cvt_pk_bf16_f32 v32, v48, v36
	v_cvt_pk_bf16_f32 v33, v37, v38
	v_cvt_pk_bf16_f32 v34, v39, v44
; __device__ __forceinline__ float sigmoidf_(float x) { return __builtin_amdgcn_rcpf(1.f + __expf(-x)); }
;     __device__ __forceinline__ void operator()(const AccT& acc, const Unit& u, int wr, int wc, int fr, int fq) const {
;         const int row0 = u.pm * BM + wr * 64 + fr, col = u.pn * 128 + wc * 32 + 8 * fq;
; #pragma unroll
;         for (int ai = 0; ai < 2; ++ai)
; #pragma unroll
;             for (int m = 0; m < 4; ++m) {
;                 const int row = row0 + ai * HALF + m * 16;
;                 const float rs = rsqrtf(ss[row] * (1.f / 1024.f) + EPS);
;                 float o[8];
; #pragma unroll
;                 for (int n = 0; n < 2; ++n)
; #pragma unroll
;                     for (int j = 0; j < 4; ++j) { const float gt = acc[ai][0][m][n][j] * rs, up = acc[ai][1][m][n][j] * rs; o[n * 4 + j] = gt * up * sigmoidf_(gt); }
;                 *(u32x4*)(O + (size_t)row * FF + col) = pack8(o);
	v_cvt_pk_bf16_f32 v35, v40, v35
	global_store_dwordx4 v[42:43], v[32:35], off
	s_nop 0
	s_nop 0
	v_mov_b32_e32 v33, v20
	v_mov_b32_e32 v20, v29
	v_mov_b32_e32 v29, v22
	v_mov_b32_e32 v22, v31
	v_mov_b32_e32 v31, v16
	v_mov_b32_e32 v16, v25
	v_mov_b32_e32 v25, v18
	v_mov_b32_e32 v18, v27
	v_mov_b32_e32 v32, v28
	v_mov_b32_e32 v28, v30
	v_mov_b32_e32 v30, v24
	v_mov_b32_e32 v24, v26
	v_add_u32_e32 v26, 0xa0, v146
	s_nop 0
	v_fmamk_f32 v27, v238, 0x3a800000, v155
	v_mul_f32_e32 v34, 0x4b800000, v27
	v_cmp_gt_f32_e32 vcc, s78, v27
	s_nop 1
	v_cndmask_b32_e32 v27, v27, v34, vcc
	v_rsq_f32_e32 v34, v27
	v_mad_i64_i32 v[26:27], s[4:5], v26, s79, v[120:121]
	v_lshl_add_u64 v[26:27], v[26:27], 0, v[122:123]
	v_mul_f32_e32 v35, 0x45800000, v34
	v_cndmask_b32_e32 v34, v34, v35, vcc
	v_pk_mul_f32 v[18:19], v[18:19], v[34:35] op_sel_hi:[1,0]
	v_pk_mul_f32 v[32:33], v[32:33], v[34:35] op_sel_hi:[1,0]
	v_pk_mul_f32 v[20:21], v[20:21], v[34:35] op_sel_hi:[1,0]
	v_pk_mul_f32 v[28:29], v[28:29], v[34:35] op_sel_hi:[1,0]
	v_pk_mul_f32 v[22:23], v[22:23], v[34:35] op_sel_hi:[1,0]
	v_pk_mul_f32 v[30:31], v[30:31], v[34:35] op_sel_hi:[1,0]
	v_pk_mul_f32 v[16:17], v[16:17], v[34:35] op_sel_hi:[1,0]
	v_pk_mul_f32 v[24:25], v[24:25], v[34:35] op_sel_hi:[1,0]
	v_mul_f32_e32 v19, v18, v19
	v_mul_f32_e32 v18, 0xbfb8aa3b, v18
	v_mul_f32_e32 v33, v32, v33
	v_mul_f32_e32 v32, 0xbfb8aa3b, v32
	v_mul_f32_e32 v21, v20, v21
	v_mul_f32_e32 v20, 0xbfb8aa3b, v20
	v_mul_f32_e32 v29, v28, v29
	v_mul_f32_e32 v28, 0xbfb8aa3b, v28
	v_mul_f32_e32 v23, v22, v23
	v_mul_f32_e32 v22, 0xbfb8aa3b, v22
	v_mul_f32_e32 v31, v30, v31
	v_mul_f32_e32 v30, 0xbfb8aa3b, v30
	v_mul_f32_e32 v17, v16, v17
	v_mul_f32_e32 v16, 0xbfb8aa3b, v16
	v_mul_f32_e32 v25, v24, v25
	v_mul_f32_e32 v24, 0xbfb8aa3b, v24
	v_exp_f32_e32 v18, v18
	v_exp_f32_e32 v32, v32
	v_exp_f32_e32 v20, v20
	v_exp_f32_e32 v28, v28
	v_exp_f32_e32 v22, v22
	v_exp_f32_e32 v30, v30
	v_exp_f32_e32 v16, v16
	v_exp_f32_e32 v24, v24
	v_add_f32_e32 v18, 1.0, v18
	v_add_f32_e32 v32, 1.0, v32
	v_add_f32_e32 v20, 1.0, v20
	v_add_f32_e32 v28, 1.0, v28
	v_add_f32_e32 v22, 1.0, v22
	v_add_f32_e32 v30, 1.0, v30
	v_add_f32_e32 v16, 1.0, v16
	v_add_f32_e32 v24, 1.0, v24
	v_rcp_f32_e32 v18, v18
	v_rcp_f32_e32 v32, v32
	v_rcp_f32_e32 v20, v20
	v_rcp_f32_e32 v28, v28
	v_rcp_f32_e32 v22, v22
	v_rcp_f32_e32 v30, v30
	v_rcp_f32_e32 v16, v16
	v_rcp_f32_e32 v24, v24
	v_mul_f32_e32 v19, v19, v18
	v_mul_f32_e32 v32, v33, v32
	v_mul_f32_e32 v20, v21, v20
	v_mul_f32_e32 v21, v29, v28
	v_mul_f32_e32 v22, v23, v22
	v_mul_f32_e32 v23, v31, v30
	v_mul_f32_e32 v28, v17, v16
	v_mul_f32_e32 v24, v25, v24
	v_cvt_pk_bf16_f32 v16, v32, v20
	v_cvt_pk_bf16_f32 v17, v21, v22
	v_cvt_pk_bf16_f32 v18, v23, v28
	v_cvt_pk_bf16_f32 v19, v24, v19
	global_store_dwordx4 v[26:27], v[16:19], off
	s_nop 0
	s_andn2_b64 vcc, exec, s[0:1]
	v_mov_b32_e32 v17, v4
	v_mov_b32_e32 v4, v13
	v_mov_b32_e32 v13, v6
	v_mov_b32_e32 v6, v15
	v_mov_b32_e32 v15, v0
	v_mov_b32_e32 v0, v9
	v_mov_b32_e32 v9, v2
	v_mov_b32_e32 v2, v11
	v_mov_b32_e32 v16, v12
	v_mov_b32_e32 v12, v14
	v_mov_b32_e32 v14, v8
	v_mov_b32_e32 v8, v10
	v_add_u32_e32 v10, 0xb0, v146
	s_mov_b64 s[0:1], -1
	s_nop 0
	v_fmamk_f32 v11, v239, 0x3a800000, v155
	v_mul_f32_e32 v18, 0x4b800000, v11
	v_cmp_gt_f32_e64 s[4:5], s78, v11
	s_nop 1
	v_cndmask_b32_e64 v11, v11, v18, s[4:5]
	v_rsq_f32_e32 v18, v11
	v_mad_i64_i32 v[10:11], s[22:23], v10, s79, v[120:121]
	v_lshl_add_u64 v[10:11], v[10:11], 0, v[122:123]
	v_mul_f32_e32 v19, 0x45800000, v18
	v_cndmask_b32_e64 v18, v18, v19, s[4:5]
	v_pk_mul_f32 v[2:3], v[2:3], v[18:19] op_sel_hi:[1,0]
	v_pk_mul_f32 v[16:17], v[16:17], v[18:19] op_sel_hi:[1,0]
	v_pk_mul_f32 v[4:5], v[4:5], v[18:19] op_sel_hi:[1,0]
	v_pk_mul_f32 v[12:13], v[12:13], v[18:19] op_sel_hi:[1,0]
	v_pk_mul_f32 v[6:7], v[6:7], v[18:19] op_sel_hi:[1,0]
	v_pk_mul_f32 v[14:15], v[14:15], v[18:19] op_sel_hi:[1,0]
	v_pk_mul_f32 v[0:1], v[0:1], v[18:19] op_sel_hi:[1,0]
	v_pk_mul_f32 v[8:9], v[8:9], v[18:19] op_sel_hi:[1,0]
	v_mul_f32_e32 v3, v2, v3
	v_mul_f32_e32 v2, 0xbfb8aa3b, v2
	v_mul_f32_e32 v17, v16, v17
	v_mul_f32_e32 v16, 0xbfb8aa3b, v16
	v_mul_f32_e32 v5, v4, v5
	v_mul_f32_e32 v4, 0xbfb8aa3b, v4
	v_mul_f32_e32 v13, v12, v13
	v_mul_f32_e32 v12, 0xbfb8aa3b, v12
	v_mul_f32_e32 v7, v6, v7
	v_mul_f32_e32 v6, 0xbfb8aa3b, v6
	v_mul_f32_e32 v15, v14, v15
	v_mul_f32_e32 v14, 0xbfb8aa3b, v14
	v_mul_f32_e32 v1, v0, v1
	v_mul_f32_e32 v0, 0xbfb8aa3b, v0
	v_mul_f32_e32 v9, v8, v9
	v_mul_f32_e32 v8, 0xbfb8aa3b, v8
	v_exp_f32_e32 v2, v2
	v_exp_f32_e32 v16, v16
	v_exp_f32_e32 v4, v4
	v_exp_f32_e32 v12, v12
	v_exp_f32_e32 v6, v6
	v_exp_f32_e32 v14, v14
	v_exp_f32_e32 v0, v0
	v_exp_f32_e32 v8, v8
	v_add_f32_e32 v2, 1.0, v2
	v_add_f32_e32 v16, 1.0, v16
	v_add_f32_e32 v4, 1.0, v4
	v_add_f32_e32 v12, 1.0, v12
	v_add_f32_e32 v6, 1.0, v6
	v_add_f32_e32 v14, 1.0, v14
	v_add_f32_e32 v0, 1.0, v0
	v_add_f32_e32 v8, 1.0, v8
	v_rcp_f32_e32 v2, v2
	v_rcp_f32_e32 v16, v16
	v_rcp_f32_e32 v4, v4
	v_rcp_f32_e32 v12, v12
	v_rcp_f32_e32 v6, v6
	v_rcp_f32_e32 v14, v14
	v_rcp_f32_e32 v0, v0
	v_rcp_f32_e32 v8, v8
	v_mul_f32_e32 v3, v3, v2
	v_mul_f32_e32 v16, v17, v16
	v_mul_f32_e32 v4, v5, v4
	v_mul_f32_e32 v5, v13, v12
	v_mul_f32_e32 v6, v7, v6
	v_mul_f32_e32 v7, v15, v14
	v_mul_f32_e32 v12, v1, v0
	v_mul_f32_e32 v8, v9, v8
	v_cvt_pk_bf16_f32 v0, v16, v4
	v_cvt_pk_bf16_f32 v1, v5, v6
	v_cvt_pk_bf16_f32 v2, v7, v12
	v_cvt_pk_bf16_f32 v3, v8, v3
	global_store_dwordx4 v[10:11], v[0:3], off
	s_cbranch_vccnz .LBB0_219
	s_andn2_b64 vcc, exec, s[6:7]
	s_cbranch_vccnz .LBB0_218
	s_barrier
	s_branch .LBB0_218

; #define PG8_STAGE(bufoff, gbase, voff) do { _Pragma("unroll") for (int _i = 0; _i < 2; ++_i) \
;         __builtin_amdgcn_global_load_lds((const unsigned*)((const char*)(gbase) + (voff)[_i]), (LAS unsigned*)(lds + (bufoff) + ldsw + _i * 8192), 16, 0, 0); } while (0)
; #define PG8_LDA(dst, b, h) do { _Pragma("unroll") for (int m = 0; m < 4; ++m) _Pragma("unroll") for (int k = 0; k < 2; ++k) dst[m][k] = *(const LAS bf16x8*)(lds + PG8_SA(b, h) + aoff + m * 2048 + k * 1024); } while (0)
; #define PG8_LDB(dst, b, h) do { _Pragma("unroll") for (int n = 0; n < 2; ++n) _Pragma("unroll") for (int k = 0; k < 2; ++k) dst[n][k] = *(const LAS bf16x8*)(lds + PG8_SB(b, h) + boff + n * 2048 + k * 1024); } while (0)
; #define PG8_WAIT_V(n) asm volatile("s_waitcnt vmcnt(" #n ")" ::: "memory")
; #define PG8_WAIT_L(n) asm volatile("s_waitcnt lgkmcnt(" #n ")" ::: "memory")
; #define PG8_BAR __builtin_amdgcn_s_barrier()
; template <class Epi>
; __device__ __forceinline__ void gemm_phase(LAS unsigned char* lds, const Gemm g, const StaticOrder& S, const Epi& E) {
;     ...
;         const bool has_next = S.next(ui + 1, nxt);
;         const char* nA = has_next ? (const char*)g.A + (size_t)nxt.pm * tsA : cA; const char* nB = has_next ? (const char*)g.Bt + (size_t)nxt.pn * tsB : cB;
;         for (int t = 0; t < nt; t += 2) {
;             const bool last = (t == nt - 2);
;             const char* a1 = cA + (size_t)(t + 1) * kstep;
;             const char* a2 = last ? nA : cA + (size_t)(t + 2) * kstep; const char* b2 = last ? nB : cB + (size_t)(t + 2) * kstep;
;             const char* a3 = a2 + kstep; const char* b3 = b2 + kstep;
;             PG8_LDB(B0, 0, 0); PG8_LDB(B1, 0, 1); PG8_SCHED; PG8_LDA(At, 0, 0); PG8_STAGE(PG8_SA(1, 1), a1 + hsA, voffA);
;             PG8_WAIT_V(8); PG8_WAIT_L(0); PG8_BAR; PG8_MMA(0, 0, At, B0); PG8_MMA(0, 1, At, B1); PG8_BAR; PG8_SCHED;
;             PG8_LDA(At, 0, 1); PG8_STAGE(PG8_SB(0, 0), b2, voffB); PG8_STAGE(PG8_SB(0, 1), b2 + hsB, voffB); PG8_STAGE(PG8_SA(0, 0), a2, voffA);
;             PG8_WAIT_V(8); PG8_WAIT_L(0); PG8_BAR; PG8_MMA(1, 0, At, B0); PG8_MMA(1, 1, At, B1); PG8_BAR; PG8_SCHED;
;     __device__ __forceinline__ void operator()(const AccT& acc, const Unit& u, int wr, int wc, int fr, int fq) const {
;     ...
;                 const int row = row0 + ai * HALF + m * 16;
;                 const float rs = rsqrtf(ss[row] * (1.f / 1024.f) + EPS);
.LBB0_422:
	s_ashr_i32 s17, s16, 31
	s_lshl_b64 s[18:19], s[16:17], 19
	s_add_u32 s18, s46, s18
	s_addc_u32 s19, s47, s19
	s_and_b64 s[20:21], s[4:5], exec
	s_cselect_b32 s7, s19, s25
	s_cselect_b32 s17, s18, s24
	s_ashr_i32 s15, s14, 31
	s_lshl_b64 s[20:21], s[14:15], 19
	s_add_u32 s20, s60, s20
	s_addc_u32 s21, s61, s21
	s_and_b64 s[56:57], s[4:5], exec
	s_cselect_b32 s15, s21, s29
	s_cselect_b32 s23, s20, s28
	s_add_u32 s24, s24, 0x40080
	s_addc_u32 s25, s25, 0
	s_add_u32 s88, s28, 0x100
	s_addc_u32 s89, s29, 0
	s_mov_b32 s90, -2
	v_lshl_add_u32 v240, s22, 8, v129
	v_ashrrev_i32_e32 v241, 31, v240
	v_lshl_add_u64 v[242:243], v[240:241], 2, s[0:1]
	global_load_dword v232, v[242:243], off
	global_load_dword v233, v[242:243], off offset:64
	global_load_dword v234, v[242:243], off offset:128
	global_load_dword v235, v[242:243], off offset:192
	global_load_dword v236, v[242:243], off offset:512
	global_load_dword v237, v[242:243], off offset:576
	global_load_dword v238, v[242:243], off offset:640
	global_load_dword v239, v[242:243], off offset:704
	ds_read_b128 v[146:149], v160
	ds_read_b128 v[150:153], v160 offset:1024
	ds_read_b128 v[168:171], v160 offset:2048
	ds_read_b128 v[172:175], v160 offset:3072
	ds_read_b128 v[176:179], v161
	ds_read_b128 v[180:183], v161 offset:1024
	ds_read_b128 v[184:187], v161 offset:2048
	ds_read_b128 v[188:191], v161 offset:3072
	s_add_u32 s28, s24, 0xfffc0080
	s_addc_u32 s29, s25, -1
	s_cmp_eq_u32 s90, 12
	s_cselect_b32 s57, s7, s29
	s_cselect_b32 s56, s17, s28
	s_cselect_b32 s29, s15, s89
	s_cselect_b32 s28, s23, s88
	v_lshl_add_u64 v[154:155], s[24:25], 0, v[138:139]
	s_add_i32 m0, s63, 0xc000
	ds_read_b128 v[192:195], v165
	ds_read_b128 v[196:199], v165 offset:1024
	ds_read_b128 v[200:203], v165 offset:2048
	ds_read_b128 v[204:207], v165 offset:3072
	ds_read_b128 v[208:211], v165 offset:4096
	ds_read_b128 v[212:215], v165 offset:5120
	ds_read_b128 v[216:219], v165 offset:6144
	ds_read_b128 v[220:223], v165 offset:7168
	global_load_lds_dwordx4 v[154:155], off
	v_lshl_add_u64 v[154:155], s[24:25], 0, v[140:141]
	s_add_i32 m0, s63, 0xe000
	s_nop 0
	global_load_lds_dwordx4 v[154:155], off
	s_waitcnt vmcnt(16)
	s_waitcnt lgkmcnt(0)
	s_barrier
	s_setprio 1
	s_waitcnt lgkmcnt(0)
	v_mfma_f32_16x16x32_bf16 v[124:127], v[146:149], v[192:195], 0
	v_mfma_f32_16x16x32_bf16 v[120:123], v[168:171], v[192:195], 0
	v_mfma_f32_16x16x32_bf16 v[108:111], v[146:149], v[200:203], 0
	v_mfma_f32_16x16x32_bf16 v[104:107], v[168:171], v[200:203], 0
	v_mfma_f32_16x16x32_bf16 v[92:95], v[146:149], v[208:211], 0
	v_mfma_f32_16x16x32_bf16 v[88:91], v[168:171], v[208:211], 0
	v_mfma_f32_16x16x32_bf16 v[76:79], v[146:149], v[216:219], 0
	v_mfma_f32_16x16x32_bf16 v[72:75], v[168:171], v[216:219], 0
	v_mfma_f32_16x16x32_bf16 v[124:127], v[150:153], v[196:199], v[124:127]
	v_mfma_f32_16x16x32_bf16 v[120:123], v[172:175], v[196:199], v[120:123]
	v_mfma_f32_16x16x32_bf16 v[108:111], v[150:153], v[204:207], v[108:111]
	v_mfma_f32_16x16x32_bf16 v[104:107], v[172:175], v[204:207], v[104:107]
	v_mfma_f32_16x16x32_bf16 v[92:95], v[150:153], v[212:215], v[92:95]
	v_mfma_f32_16x16x32_bf16 v[88:91], v[172:175], v[212:215], v[88:91]
	v_mfma_f32_16x16x32_bf16 v[76:79], v[150:153], v[220:223], v[76:79]
	v_mfma_f32_16x16x32_bf16 v[72:75], v[172:175], v[220:223], v[72:75]
	s_setprio 0
	s_setprio 1
	v_mfma_f32_16x16x32_bf16 v[116:119], v[176:179], v[192:195], 0
	v_mfma_f32_16x16x32_bf16 v[112:115], v[184:187], v[192:195], 0
	v_mfma_f32_16x16x32_bf16 v[100:103], v[176:179], v[200:203], 0
	v_mfma_f32_16x16x32_bf16 v[96:99], v[184:187], v[200:203], 0
	v_mfma_f32_16x16x32_bf16 v[84:87], v[176:179], v[208:211], 0
	v_mfma_f32_16x16x32_bf16 v[80:83], v[184:187], v[208:211], 0
	v_mfma_f32_16x16x32_bf16 v[68:71], v[176:179], v[216:219], 0
	v_mfma_f32_16x16x32_bf16 v[64:67], v[184:187], v[216:219], 0
	v_mfma_f32_16x16x32_bf16 v[116:119], v[180:183], v[196:199], v[116:119]
	v_mfma_f32_16x16x32_bf16 v[112:115], v[188:191], v[196:199], v[112:115]
	v_mfma_f32_16x16x32_bf16 v[100:103], v[180:183], v[204:207], v[100:103]
	v_mfma_f32_16x16x32_bf16 v[96:99], v[188:191], v[204:207], v[96:99]
	v_mfma_f32_16x16x32_bf16 v[84:87], v[180:183], v[212:215], v[84:87]
	v_mfma_f32_16x16x32_bf16 v[80:83], v[188:191], v[212:215], v[80:83]
	v_mfma_f32_16x16x32_bf16 v[68:71], v[180:183], v[220:223], v[68:71]
	v_mfma_f32_16x16x32_bf16 v[64:67], v[188:191], v[220:223], v[64:67]
	s_setprio 0
	s_barrier
	s_add_i32 s33, s83, s62
	v_lshl_add_u64 v[154:155], s[28:29], 0, v[132:133]
	s_mov_b32 m0, s33
	ds_read_b128 v[192:195], v165 offset:16384
	ds_read_b128 v[196:199], v165 offset:17408
	ds_read_b128 v[200:203], v165 offset:18432
	ds_read_b128 v[204:207], v165 offset:19456
	ds_read_b128 v[208:211], v165 offset:20480
	ds_read_b128 v[212:215], v165 offset:21504
	ds_read_b128 v[216:219], v165 offset:22528
	ds_read_b128 v[220:223], v165 offset:23552
	global_load_lds_dwordx4 v[154:155], off
	s_add_i32 m0, s33, 0x2000
	s_add_u32 s92, s28, 0x40000
	v_lshl_add_u64 v[224:225], s[28:29], 0, v[136:137]
	s_addc_u32 s93, s29, 0
	s_add_i32 s33, s84, s62
	global_load_lds_dwordx4 v[224:225], off
	v_lshl_add_u64 v[226:227], s[92:93], 0, v[132:133]
	s_mov_b32 m0, s33
	v_lshl_add_u64 v[228:229], s[56:57], 0, v[134:135]
	global_load_lds_dwordx4 v[226:227], off
	v_lshl_add_u64 v[226:227], s[92:93], 0, v[136:137]
	s_add_i32 m0, s33, 0x2000
	s_nop 0
	global_load_lds_dwordx4 v[226:227], off
	v_lshl_add_u64 v[226:227], s[56:57], 0, v[130:131]
	s_mov_b32 m0, s63
	s_nop 0
	global_load_lds_dwordx4 v[226:227], off
	s_mov_b32 m0, s64
	s_nop 0
	global_load_lds_dwordx4 v[228:229], off
	s_waitcnt vmcnt(8)
	s_waitcnt lgkmcnt(0)
	s_barrier
; #define PG8_STAGE(bufoff, gbase, voff) do { _Pragma("unroll") for (int _i = 0; _i < 2; ++_i) \
;         __builtin_amdgcn_global_load_lds((const unsigned*)((const char*)(gbase) + (voff)[_i]), (LAS unsigned*)(lds + (bufoff) + ldsw + _i * 8192), 16, 0, 0); } while (0)
; #define PG8_LDA(dst, b, h) do { _Pragma("unroll") for (int m = 0; m < 4; ++m) _Pragma("unroll") for (int k = 0; k < 2; ++k) dst[m][k] = *(const LAS bf16x8*)(lds + PG8_SA(b, h) + aoff + m * 2048 + k * 1024); } while (0)
; #define PG8_LDB(dst, b, h) do { _Pragma("unroll") for (int n = 0; n < 2; ++n) _Pragma("unroll") for (int k = 0; k < 2; ++k) dst[n][k] = *(const LAS bf16x8*)(lds + PG8_SB(b, h) + boff + n * 2048 + k * 1024); } while (0)
; #define PG8_MMA(ai, bj, At, Bt) do { __builtin_amdgcn_s_setprio(1); _Pragma("unroll") for (int m = 0; m < 4; ++m) _Pragma("unroll") for (int n = 0; n < 2; ++n) _Pragma("unroll") for (int k = 0; k < 2; ++k) \
;         acc[ai][bj][m][n] = __builtin_amdgcn_mfma_f32_16x16x32_bf16(Bt[n][k], At[m][k], acc[ai][bj][m][n], 0, 0, 0); __builtin_amdgcn_s_setprio(0); } while (0)
; #define PG8_WAIT_V(n) asm volatile("s_waitcnt vmcnt(" #n ")" ::: "memory")
; #define PG8_WAIT_L(n) asm volatile("s_waitcnt lgkmcnt(" #n ")" ::: "memory")
; #define PG8_BAR __builtin_amdgcn_s_barrier()
; #define PG8_SCHED __builtin_amdgcn_sched_barrier(0)
; template <class Epi>
; __device__ __forceinline__ void gemm_phase(LAS unsigned char* lds, const Gemm g, const StaticOrder& S, const Epi& E) {
;     ...
;             PG8_WAIT_V(8); PG8_WAIT_L(0); PG8_BAR; PG8_MMA(1, 0, At, B0); PG8_MMA(1, 1, At, B1); PG8_BAR; PG8_SCHED;
;             PG8_LDB(B0, 1, 0); PG8_LDB(B1, 1, 1); PG8_SCHED; PG8_LDA(At, 1, 0); PG8_STAGE(PG8_SA(0, 1), a2 + hsA, voffA);
;             PG8_WAIT_V(8); PG8_WAIT_L(0); PG8_BAR; PG8_MMA(0, 0, At, B0); PG8_MMA(0, 1, At, B1); PG8_BAR; PG8_SCHED;
	s_setprio 1
	s_waitcnt lgkmcnt(0)
	v_mfma_f32_16x16x32_bf16 v[60:63], v[146:149], v[192:195], 0
	v_mfma_f32_16x16x32_bf16 v[56:59], v[168:171], v[192:195], 0
	v_mfma_f32_16x16x32_bf16 v[44:47], v[146:149], v[200:203], 0
	v_mfma_f32_16x16x32_bf16 v[40:43], v[168:171], v[200:203], 0
	v_mfma_f32_16x16x32_bf16 v[28:31], v[146:149], v[208:211], 0
	v_mfma_f32_16x16x32_bf16 v[24:27], v[168:171], v[208:211], 0
	v_mfma_f32_16x16x32_bf16 v[12:15], v[146:149], v[216:219], 0
	v_mfma_f32_16x16x32_bf16 v[8:11], v[168:171], v[216:219], 0
	v_mfma_f32_16x16x32_bf16 v[60:63], v[150:153], v[196:199], v[60:63]
	v_mfma_f32_16x16x32_bf16 v[56:59], v[172:175], v[196:199], v[56:59]
	v_mfma_f32_16x16x32_bf16 v[44:47], v[150:153], v[204:207], v[44:47]
	v_mfma_f32_16x16x32_bf16 v[40:43], v[172:175], v[204:207], v[40:43]
	v_mfma_f32_16x16x32_bf16 v[28:31], v[150:153], v[212:215], v[28:31]
	v_mfma_f32_16x16x32_bf16 v[24:27], v[172:175], v[212:215], v[24:27]
	v_mfma_f32_16x16x32_bf16 v[12:15], v[150:153], v[220:223], v[12:15]
	v_mfma_f32_16x16x32_bf16 v[8:11], v[172:175], v[220:223], v[8:11]
	s_setprio 0
	s_setprio 1
	v_mfma_f32_16x16x32_bf16 v[52:55], v[176:179], v[192:195], 0
	v_mfma_f32_16x16x32_bf16 v[48:51], v[184:187], v[192:195], 0
	v_mfma_f32_16x16x32_bf16 v[36:39], v[176:179], v[200:203], 0
	v_mfma_f32_16x16x32_bf16 v[32:35], v[184:187], v[200:203], 0
	v_mfma_f32_16x16x32_bf16 v[20:23], v[176:179], v[208:211], 0
	v_mfma_f32_16x16x32_bf16 v[16:19], v[184:187], v[208:211], 0
	v_mfma_f32_16x16x32_bf16 v[4:7], v[176:179], v[216:219], 0
	v_mfma_f32_16x16x32_bf16 v[0:3], v[184:187], v[216:219], 0
	v_mfma_f32_16x16x32_bf16 v[52:55], v[180:183], v[196:199], v[52:55]
	v_mfma_f32_16x16x32_bf16 v[48:51], v[188:191], v[196:199], v[48:51]
	v_mfma_f32_16x16x32_bf16 v[36:39], v[180:183], v[204:207], v[36:39]
	v_mfma_f32_16x16x32_bf16 v[32:35], v[188:191], v[204:207], v[32:35]
	v_mfma_f32_16x16x32_bf16 v[20:23], v[180:183], v[212:215], v[20:23]
	v_mfma_f32_16x16x32_bf16 v[16:19], v[188:191], v[212:215], v[16:19]
	v_mfma_f32_16x16x32_bf16 v[4:7], v[180:183], v[220:223], v[4:7]
	v_mfma_f32_16x16x32_bf16 v[0:3], v[188:191], v[220:223], v[0:3]
	s_setprio 0
	s_barrier
	s_add_i32 s33, 0, 0x18000
	s_add_i32 s91, 0, 0x1c000
	v_add_u32_e32 v172, s33, v158
	v_add_u32_e32 v188, s91, v158
	ds_read_b128 v[146:149], v172
	ds_read_b128 v[150:153], v172 offset:1024
	ds_read_b128 v[168:171], v172 offset:2048
	ds_read_b128 v[172:175], v172 offset:3072
	ds_read_b128 v[176:179], v188
	ds_read_b128 v[180:183], v188 offset:1024
	ds_read_b128 v[184:187], v188 offset:2048
	ds_read_b128 v[188:191], v188 offset:3072
	s_add_u32 s56, s56, 0x40000
	s_addc_u32 s57, s57, 0
	s_mov_b32 m0, s65
	v_lshl_add_u64 v[230:231], s[56:57], 0, v[130:131]
	ds_read_b128 v[192:195], v165 offset:32768
	ds_read_b128 v[196:199], v165 offset:33792
	ds_read_b128 v[200:203], v165 offset:34816
	ds_read_b128 v[204:207], v165 offset:35840
	ds_read_b128 v[208:211], v165 offset:36864
	ds_read_b128 v[212:215], v165 offset:37888
	ds_read_b128 v[216:219], v165 offset:38912
	ds_read_b128 v[220:223], v165 offset:39936
	global_load_lds_dwordx4 v[230:231], off
	v_lshl_add_u64 v[230:231], s[56:57], 0, v[134:135]
	s_mov_b32 m0, s66
	s_nop 0
	global_load_lds_dwordx4 v[230:231], off
	s_waitcnt vmcnt(8)
	s_waitcnt lgkmcnt(0)
	s_barrier
	s_setprio 1
	s_waitcnt lgkmcnt(0)
	v_mfma_f32_16x16x32_bf16 v[124:127], v[146:149], v[192:195], v[124:127]
	v_mfma_f32_16x16x32_bf16 v[120:123], v[168:171], v[192:195], v[120:123]
	v_mfma_f32_16x16x32_bf16 v[108:111], v[146:149], v[200:203], v[108:111]
	v_mfma_f32_16x16x32_bf16 v[104:107], v[168:171], v[200:203], v[104:107]
	v_mfma_f32_16x16x32_bf16 v[92:95], v[146:149], v[208:211], v[92:95]
	v_mfma_f32_16x16x32_bf16 v[88:91], v[168:171], v[208:211], v[88:91]
	v_mfma_f32_16x16x32_bf16 v[76:79], v[146:149], v[216:219], v[76:79]
	v_mfma_f32_16x16x32_bf16 v[72:75], v[168:171], v[216:219], v[72:75]
	v_mfma_f32_16x16x32_bf16 v[124:127], v[150:153], v[196:199], v[124:127]
	v_mfma_f32_16x16x32_bf16 v[120:123], v[172:175], v[196:199], v[120:123]
	v_mfma_f32_16x16x32_bf16 v[108:111], v[150:153], v[204:207], v[108:111]
	v_mfma_f32_16x16x32_bf16 v[104:107], v[172:175], v[204:207], v[104:107]
	v_mfma_f32_16x16x32_bf16 v[92:95], v[150:153], v[212:215], v[92:95]
	v_mfma_f32_16x16x32_bf16 v[88:91], v[172:175], v[212:215], v[88:91]
	v_mfma_f32_16x16x32_bf16 v[76:79], v[150:153], v[220:223], v[76:79]
	v_mfma_f32_16x16x32_bf16 v[72:75], v[172:175], v[220:223], v[72:75]
	s_setprio 0
	s_setprio 1
	v_mfma_f32_16x16x32_bf16 v[116:119], v[176:179], v[192:195], v[116:119]
	v_mfma_f32_16x16x32_bf16 v[112:115], v[184:187], v[192:195], v[112:115]
	v_mfma_f32_16x16x32_bf16 v[100:103], v[176:179], v[200:203], v[100:103]
	v_mfma_f32_16x16x32_bf16 v[96:99], v[184:187], v[200:203], v[96:99]
	v_mfma_f32_16x16x32_bf16 v[84:87], v[176:179], v[208:211], v[84:87]
	v_mfma_f32_16x16x32_bf16 v[80:83], v[184:187], v[208:211], v[80:83]
	v_mfma_f32_16x16x32_bf16 v[68:71], v[176:179], v[216:219], v[68:71]
	v_mfma_f32_16x16x32_bf16 v[64:67], v[184:187], v[216:219], v[64:67]
	v_mfma_f32_16x16x32_bf16 v[116:119], v[180:183], v[196:199], v[116:119]
	v_mfma_f32_16x16x32_bf16 v[112:115], v[188:191], v[196:199], v[112:115]
	v_mfma_f32_16x16x32_bf16 v[100:103], v[180:183], v[204:207], v[100:103]
	v_mfma_f32_16x16x32_bf16 v[96:99], v[188:191], v[204:207], v[96:99]
	v_mfma_f32_16x16x32_bf16 v[84:87], v[180:183], v[212:215], v[84:87]
	v_mfma_f32_16x16x32_bf16 v[80:83], v[188:191], v[212:215], v[80:83]
	v_mfma_f32_16x16x32_bf16 v[68:71], v[180:183], v[220:223], v[68:71]
	v_mfma_f32_16x16x32_bf16 v[64:67], v[188:191], v[220:223], v[64:67]
	s_setprio 0
	s_barrier
; #define PG8_STAGE(bufoff, gbase, voff) do { _Pragma("unroll") for (int _i = 0; _i < 2; ++_i) \
;         __builtin_amdgcn_global_load_lds((const unsigned*)((const char*)(gbase) + (voff)[_i]), (LAS unsigned*)(lds + (bufoff) + ldsw + _i * 8192), 16, 0, 0); } while (0)
; #define PG8_LDA(dst, b, h) do { _Pragma("unroll") for (int m = 0; m < 4; ++m) _Pragma("unroll") for (int k = 0; k < 2; ++k) dst[m][k] = *(const LAS bf16x8*)(lds + PG8_SA(b, h) + aoff + m * 2048 + k * 1024); } while (0)
; #define PG8_MMA(ai, bj, At, Bt) do { __builtin_amdgcn_s_setprio(1); _Pragma("unroll") for (int m = 0; m < 4; ++m) _Pragma("unroll") for (int n = 0; n < 2; ++n) _Pragma("unroll") for (int k = 0; k < 2; ++k) \
;         acc[ai][bj][m][n] = __builtin_amdgcn_mfma_f32_16x16x32_bf16(Bt[n][k], At[m][k], acc[ai][bj][m][n], 0, 0, 0); __builtin_amdgcn_s_setprio(0); } while (0)
; #define PG8_WAIT_V(n) asm volatile("s_waitcnt vmcnt(" #n ")" ::: "memory")
; #define PG8_WAIT_L(n) asm volatile("s_waitcnt lgkmcnt(" #n ")" ::: "memory")
; #define PG8_BAR __builtin_amdgcn_s_barrier()
; #define PG8_SCHED __builtin_amdgcn_sched_barrier(0)
; template <class Epi>
; __device__ __forceinline__ void gemm_phase(LAS unsigned char* lds, const Gemm g, const StaticOrder& S, const Epi& E) {
;     ...
;         for (int t = 0; t < nt; t += 2) {
;     ...
;             PG8_LDA(At, 1, 1); PG8_STAGE(PG8_SB(1, 0), b3, voffB); PG8_STAGE(PG8_SB(1, 1), b3 + hsB, voffB); PG8_STAGE(PG8_SA(1, 0), a3, voffA);
;             PG8_WAIT_V(8); PG8_WAIT_L(0); PG8_BAR; PG8_MMA(1, 0, At, B0); PG8_MMA(1, 1, At, B1); PG8_BAR; PG8_SCHED;
	s_add_i32 s33, s33, s62
	v_lshl_add_u64 v[154:155], v[154:155], 0, s[10:11]
	s_mov_b32 m0, s33
	ds_read_b128 v[192:195], v165 offset:49152
	ds_read_b128 v[196:199], v165 offset:50176
	ds_read_b128 v[200:203], v165 offset:51200
	ds_read_b128 v[204:207], v165 offset:52224
	ds_read_b128 v[208:211], v165 offset:53248
	ds_read_b128 v[212:215], v165 offset:54272
	ds_read_b128 v[216:219], v165 offset:55296
	ds_read_b128 v[220:223], v165 offset:56320
	global_load_lds_dwordx4 v[154:155], off
	s_add_i32 m0, s33, 0x2000
	s_add_u32 s28, s28, 0x40080
	v_lshl_add_u64 v[154:155], v[224:225], 0, s[10:11]
	s_addc_u32 s29, s29, 0
	s_add_i32 s33, s91, s62
	global_load_lds_dwordx4 v[154:155], off
	v_lshl_add_u64 v[154:155], s[28:29], 0, v[132:133]
	s_mov_b32 m0, s33
	s_nop 0
	global_load_lds_dwordx4 v[154:155], off
	v_lshl_add_u64 v[154:155], s[28:29], 0, v[136:137]
	s_add_i32 m0, s33, 0x2000
	s_nop 0
	global_load_lds_dwordx4 v[154:155], off
	v_lshl_add_u64 v[154:155], v[226:227], 0, s[10:11]
	s_mov_b32 m0, s76
	s_nop 0
	global_load_lds_dwordx4 v[154:155], off
	v_lshl_add_u64 v[154:155], v[228:229], 0, s[10:11]
	s_mov_b32 m0, s77
	s_nop 0
	global_load_lds_dwordx4 v[154:155], off
	s_waitcnt vmcnt(8)
	s_waitcnt lgkmcnt(0)
	s_barrier
	s_setprio 1
	s_waitcnt lgkmcnt(0)
	v_mfma_f32_16x16x32_bf16 v[60:63], v[146:149], v[192:195], v[60:63]
	v_mfma_f32_16x16x32_bf16 v[56:59], v[168:171], v[192:195], v[56:59]
	v_mfma_f32_16x16x32_bf16 v[44:47], v[146:149], v[200:203], v[44:47]
	v_mfma_f32_16x16x32_bf16 v[40:43], v[168:171], v[200:203], v[40:43]
	v_mfma_f32_16x16x32_bf16 v[28:31], v[146:149], v[208:211], v[28:31]
	v_mfma_f32_16x16x32_bf16 v[24:27], v[168:171], v[208:211], v[24:27]
	v_mfma_f32_16x16x32_bf16 v[12:15], v[146:149], v[216:219], v[12:15]
	v_mfma_f32_16x16x32_bf16 v[8:11], v[168:171], v[216:219], v[8:11]
	v_mfma_f32_16x16x32_bf16 v[60:63], v[150:153], v[196:199], v[60:63]
	v_mfma_f32_16x16x32_bf16 v[56:59], v[172:175], v[196:199], v[56:59]
	v_mfma_f32_16x16x32_bf16 v[44:47], v[150:153], v[204:207], v[44:47]
	v_mfma_f32_16x16x32_bf16 v[40:43], v[172:175], v[204:207], v[40:43]
	v_mfma_f32_16x16x32_bf16 v[28:31], v[150:153], v[212:215], v[28:31]
	v_mfma_f32_16x16x32_bf16 v[24:27], v[172:175], v[212:215], v[24:27]
	v_mfma_f32_16x16x32_bf16 v[12:15], v[150:153], v[220:223], v[12:15]
	v_mfma_f32_16x16x32_bf16 v[8:11], v[172:175], v[220:223], v[8:11]
	s_setprio 0
	s_setprio 1
	v_mfma_f32_16x16x32_bf16 v[52:55], v[176:179], v[192:195], v[52:55]
	v_mfma_f32_16x16x32_bf16 v[48:51], v[184:187], v[192:195], v[48:51]
	v_mfma_f32_16x16x32_bf16 v[36:39], v[176:179], v[200:203], v[36:39]
	v_mfma_f32_16x16x32_bf16 v[32:35], v[184:187], v[200:203], v[32:35]
	v_mfma_f32_16x16x32_bf16 v[20:23], v[176:179], v[208:211], v[20:23]
	v_mfma_f32_16x16x32_bf16 v[16:19], v[184:187], v[208:211], v[16:19]
	v_mfma_f32_16x16x32_bf16 v[4:7], v[176:179], v[216:219], v[4:7]
	v_mfma_f32_16x16x32_bf16 v[0:3], v[184:187], v[216:219], v[0:3]
	v_mfma_f32_16x16x32_bf16 v[52:55], v[180:183], v[196:199], v[52:55]
	v_mfma_f32_16x16x32_bf16 v[48:51], v[188:191], v[196:199], v[48:51]
	v_mfma_f32_16x16x32_bf16 v[36:39], v[180:183], v[204:207], v[36:39]
	v_mfma_f32_16x16x32_bf16 v[32:35], v[188:191], v[204:207], v[32:35]
	v_mfma_f32_16x16x32_bf16 v[20:23], v[180:183], v[212:215], v[20:23]
	v_mfma_f32_16x16x32_bf16 v[16:19], v[188:191], v[212:215], v[16:19]
	v_mfma_f32_16x16x32_bf16 v[4:7], v[180:183], v[220:223], v[4:7]
	v_mfma_f32_16x16x32_bf16 v[0:3], v[188:191], v[220:223], v[0:3]
	s_setprio 0
	s_barrier
	s_add_i32 s90, s90, 2
	s_add_u32 s24, s24, 0x100
	s_addc_u32 s25, s25, 0
	s_add_u32 s88, s88, 0x100
	s_addc_u32 s89, s89, 0
	s_cmp_gt_u32 s90, 13
	s_cbranch_scc0 .LBB0_423
	s_branch .Lpeel_exit2

; __device__ __forceinline__ unsigned cvt_pk_bf16(float lo, float hi) { unsigned r; asm volatile("v_cvt_pk_bf16_f32 %0, %1, %2" : "=v"(r) : "v"(lo), "v"(hi)); return r; }
;     __device__ __forceinline__ void operator()(const AccT& acc, const Unit& u, int wr, int wc, int fr, int fq) const {
;     ...
;                 const int row = row0 + ai * HALF + m * 16;
;                 const float rs = rsqrtf(ss[row] * (1.f / 1024.f) + EPS);
; #pragma unroll
;                 for (int bj = 0; bj < 2; ++bj) {
;                     const int col = col0 + bj * HALF;
;                     const f32x4 v0 = acc[ai][bj][m][0] * rs, v1 = acc[ai][bj][m][1] * rs;
;                     u32x4 w; w.x = cvt_pk_bf16(v0[0], v0[1]); w.y = cvt_pk_bf16(v0[2], v0[3]); w.z = cvt_pk_bf16(v1[0], v1[1]); w.w = cvt_pk_bf16(v1[2], v1[3]);
;                     *(u32x4*)(P + (size_t)row * LDP + col) = w;
;                     if (col >= C_SM && col < C_SM + 16) { float* s = SM + (size_t)row * 16 + (col - C_SM); *(f32x4*)s = v0; *(f32x4*)(s + 4) = v1; }
.LBB0_426:
	v_lshl_add_u32 v148, s22, 8, v129
	v_ashrrev_i32_e32 v149, 31, v148
	v_lshl_add_u64 v[150:151], v[148:149], 2, s[0:1]
	s_lshl_b32 s15, s6, 8
	v_mov_b64_e32 v[152:153], s[44:45]
	v_or_b32_e32 v146, s15, v159
	v_mad_i64_i32 v[152:153], s[6:7], v148, s86, v[152:153]
	v_bitop3_b32 v155, s15, v167, v159 bitop3:0xc8
	v_cmp_eq_u32_e64 s[6:7], s87, v155
	s_nop 0
	v_fmamk_f32 v147, v232, 0x3a800000, v166
	v_mul_f32_e32 v154, 0x4b800000, v147
	v_cmp_gt_f32_e32 vcc, s85, v147
	s_nop 1
	v_cndmask_b32_e32 v147, v147, v154, vcc
	v_rsq_f32_e32 v154, v147
	v_ashrrev_i32_e32 v147, 31, v146
	v_lshl_add_u64 v[152:153], v[146:147], 1, v[152:153]
	v_mul_f32_e32 v168, 0x45800000, v154
	v_cndmask_b32_e32 v154, v154, v168, vcc
	v_pk_mul_f32 v[126:127], v[126:127], v[154:155] op_sel_hi:[1,0]
	v_pk_mul_f32 v[124:125], v[124:125], v[154:155] op_sel_hi:[1,0]
	v_pk_mul_f32 v[122:123], v[122:123], v[154:155] op_sel_hi:[1,0]
	v_pk_mul_f32 v[120:121], v[120:121], v[154:155] op_sel_hi:[1,0]
	v_cvt_pk_bf16_f32 v168, v124, v125
	v_cvt_pk_bf16_f32 v169, v126, v127
	s_nop 0
	v_cvt_pk_bf16_f32 v170, v120, v121
	v_cvt_pk_bf16_f32 v171, v122, v123
	global_store_dwordx4 v[152:153], v[168:171], off
	s_and_saveexec_b64 s[22:23], s[6:7]
	s_cbranch_execz .LBB0_428
	v_lshlrev_b64 v[168:169], 6, v[148:149]
	v_lshl_add_u64 v[168:169], s[58:59], 0, v[168:169]
	v_lshl_add_u64 v[168:169], v[146:147], 2, v[168:169]
	v_add_co_u32_e32 v168, vcc, 0xffffc000, v168
	s_nop 1
	v_addc_co_u32_e32 v169, vcc, -1, v169, vcc
	global_store_dwordx4 v[168:169], v[124:127], off offset:-3328
	global_store_dwordx4 v[168:169], v[120:123], off offset:-3312

; #define PG8_STAGE(bufoff, gbase, voff) do { _Pragma("unroll") for (int _i = 0; _i < 2; ++_i) \
;         __builtin_amdgcn_global_load_lds((const unsigned*)((const char*)(gbase) + (voff)[_i]), (LAS unsigned*)(lds + (bufoff) + ldsw + _i * 8192), 16, 0, 0); } while (0)
; #define PG8_LDA(dst, b, h) do { _Pragma("unroll") for (int m = 0; m < 4; ++m) _Pragma("unroll") for (int k = 0; k < 2; ++k) dst[m][k] = *(const LAS bf16x8*)(lds + PG8_SA(b, h) + aoff + m * 2048 + k * 1024); } while (0)
; #define PG8_LDB(dst, b, h) do { _Pragma("unroll") for (int n = 0; n < 2; ++n) _Pragma("unroll") for (int k = 0; k < 2; ++k) dst[n][k] = *(const LAS bf16x8*)(lds + PG8_SB(b, h) + boff + n * 2048 + k * 1024); } while (0)
; #define PG8_MMA(ai, bj, At, Bt) do { __builtin_amdgcn_s_setprio(1); _Pragma("unroll") for (int m = 0; m < 4; ++m) _Pragma("unroll") for (int n = 0; n < 2; ++n) _Pragma("unroll") for (int k = 0; k < 2; ++k) \
;         acc[ai][bj][m][n] = __builtin_amdgcn_mfma_f32_16x16x32_bf16(Bt[n][k], At[m][k], acc[ai][bj][m][n], 0, 0, 0); __builtin_amdgcn_s_setprio(0); } while (0)
; #define PG8_WAIT_V(n) asm volatile("s_waitcnt vmcnt(" #n ")" ::: "memory")
; template <class Epi>
; __device__ __forceinline__ void gemm_phase(LAS unsigned char* lds, const Gemm g, const StaticOrder& S, const Epi& E) {
;     ...
;         for (int t = 0; t < nt; t += 2) {
;             const bool last = (t == nt - 2);
;             const char* a1 = cA + (size_t)(t + 1) * kstep;
;             const char* a2 = last ? nA : cA + (size_t)(t + 2) * kstep; const char* b2 = last ? nB : cB + (size_t)(t + 2) * kstep;
;             const char* a3 = a2 + kstep; const char* b3 = b2 + kstep;
;             PG8_LDB(B0, 0, 0); PG8_LDB(B1, 0, 1); PG8_SCHED; PG8_LDA(At, 0, 0); PG8_STAGE(PG8_SA(1, 1), a1 + hsA, voffA);
;             PG8_WAIT_V(8); PG8_WAIT_L(0); PG8_BAR; PG8_MMA(0, 0, At, B0); PG8_MMA(0, 1, At, B1); PG8_BAR; PG8_SCHED;
;             PG8_LDA(At, 0, 1); PG8_STAGE(PG8_SB(0, 0), b2, voffB); PG8_STAGE(PG8_SB(0, 1), b2 + hsB, voffB); PG8_STAGE(PG8_SA(0, 0), a2, voffA);
;             PG8_WAIT_V(8); PG8_WAIT_L(0); PG8_BAR; PG8_MMA(1, 0, At, B0); PG8_MMA(1, 1, At, B1); PG8_BAR; PG8_SCHED;
;     __device__ __forceinline__ void operator()(const AccT& acc, const Unit& u, int wr, int wc, int fr, int fq) const {
;     ...
;                 const float rs = rsqrtf(ss[row] * (1.f / 1024.f) + EPS);
.LBB0_1557:
	s_ashr_i32 s17, s16, 31
	s_lshl_b64 s[18:19], s[16:17], 19
	s_add_u32 s18, s46, s18
	s_addc_u32 s19, s47, s19
	s_and_b64 s[20:21], s[4:5], exec
	s_cselect_b32 s17, s19, s23
	s_cselect_b32 s56, s18, s22
	s_ashr_i32 s15, s14, 31
	s_lshl_b64 s[20:21], s[14:15], 19
	s_add_u32 s20, s28, s20
	s_addc_u32 s21, s29, s21
	s_and_b64 s[26:27], s[4:5], exec
	s_cselect_b32 s15, s21, s25
	s_cselect_b32 s57, s20, s24
	s_add_u32 s22, s22, 0x40080
	s_addc_u32 s23, s23, 0
	s_add_u32 s58, s24, 0x100
	s_addc_u32 s59, s25, 0
	s_mov_b32 s60, -2
	v_lshl_add_u32 v240, s0, 8, v148
	v_ashrrev_i32_e32 v241, 31, v240
	v_lshl_add_u64 v[242:243], v[240:241], 2, s[8:9]
	global_load_dword v232, v[242:243], off
	global_load_dword v233, v[242:243], off offset:64
	global_load_dword v234, v[242:243], off offset:128
	global_load_dword v235, v[242:243], off offset:192
	global_load_dword v236, v[242:243], off offset:512
	global_load_dword v237, v[242:243], off offset:576
	global_load_dword v238, v[242:243], off offset:640
	global_load_dword v239, v[242:243], off offset:704
	ds_read_b128 v[144:147], v151
	ds_read_b128 v[158:161], v151 offset:1024
	ds_read_b128 v[162:165], v151 offset:2048
	ds_read_b128 v[166:169], v151 offset:3072
	ds_read_b128 v[170:173], v152
	ds_read_b128 v[174:177], v152 offset:1024
	ds_read_b128 v[178:181], v152 offset:2048
	ds_read_b128 v[182:185], v152 offset:3072
	s_add_u32 s24, s22, 0xfffc0080
	s_addc_u32 s25, s23, -1
	s_cmp_eq_u32 s60, 12
	s_cselect_b32 s27, s17, s25
	s_cselect_b32 s26, s56, s24
	s_cselect_b32 s25, s15, s59
	s_cselect_b32 s24, s57, s58
	v_lshl_add_u64 v[218:219], s[22:23], 0, v[136:137]
	s_add_i32 m0, s39, 0xc000
	ds_read_b128 v[186:189], v153
	ds_read_b128 v[190:193], v153 offset:1024
	ds_read_b128 v[194:197], v153 offset:2048
	ds_read_b128 v[198:201], v153 offset:3072
	ds_read_b128 v[202:205], v153 offset:4096
	ds_read_b128 v[206:209], v153 offset:5120
	ds_read_b128 v[210:213], v153 offset:6144
	ds_read_b128 v[214:217], v153 offset:7168
	global_load_lds_dwordx4 v[218:219], off
	v_lshl_add_u64 v[218:219], s[22:23], 0, v[138:139]
	s_add_i32 m0, s39, 0xe000
	s_nop 0
	global_load_lds_dwordx4 v[218:219], off
	s_waitcnt vmcnt(16)
	s_waitcnt lgkmcnt(0)
	s_barrier
	s_setprio 1
	s_waitcnt lgkmcnt(0)
	v_mfma_f32_16x16x32_bf16 v[124:127], v[144:147], v[186:189], 0
	v_mfma_f32_16x16x32_bf16 v[120:123], v[162:165], v[186:189], 0
	v_mfma_f32_16x16x32_bf16 v[108:111], v[144:147], v[194:197], 0
	v_mfma_f32_16x16x32_bf16 v[104:107], v[162:165], v[194:197], 0
	v_mfma_f32_16x16x32_bf16 v[92:95], v[144:147], v[202:205], 0
	v_mfma_f32_16x16x32_bf16 v[88:91], v[162:165], v[202:205], 0
	v_mfma_f32_16x16x32_bf16 v[76:79], v[144:147], v[210:213], 0
	v_mfma_f32_16x16x32_bf16 v[72:75], v[162:165], v[210:213], 0
	v_mfma_f32_16x16x32_bf16 v[124:127], v[158:161], v[190:193], v[124:127]
	v_mfma_f32_16x16x32_bf16 v[120:123], v[166:169], v[190:193], v[120:123]
	v_mfma_f32_16x16x32_bf16 v[108:111], v[158:161], v[198:201], v[108:111]
	v_mfma_f32_16x16x32_bf16 v[104:107], v[166:169], v[198:201], v[104:107]
	v_mfma_f32_16x16x32_bf16 v[92:95], v[158:161], v[206:209], v[92:95]
	v_mfma_f32_16x16x32_bf16 v[88:91], v[166:169], v[206:209], v[88:91]
	v_mfma_f32_16x16x32_bf16 v[76:79], v[158:161], v[214:217], v[76:79]
	v_mfma_f32_16x16x32_bf16 v[72:75], v[166:169], v[214:217], v[72:75]
	s_setprio 0
	s_setprio 1
	v_mfma_f32_16x16x32_bf16 v[116:119], v[170:173], v[186:189], 0
	v_mfma_f32_16x16x32_bf16 v[112:115], v[178:181], v[186:189], 0
	v_mfma_f32_16x16x32_bf16 v[100:103], v[170:173], v[194:197], 0
	v_mfma_f32_16x16x32_bf16 v[96:99], v[178:181], v[194:197], 0
	v_mfma_f32_16x16x32_bf16 v[84:87], v[170:173], v[202:205], 0
	v_mfma_f32_16x16x32_bf16 v[80:83], v[178:181], v[202:205], 0
	v_mfma_f32_16x16x32_bf16 v[68:71], v[170:173], v[210:213], 0
	v_mfma_f32_16x16x32_bf16 v[64:67], v[178:181], v[210:213], 0
	v_mfma_f32_16x16x32_bf16 v[116:119], v[174:177], v[190:193], v[116:119]
	v_mfma_f32_16x16x32_bf16 v[112:115], v[182:185], v[190:193], v[112:115]
	v_mfma_f32_16x16x32_bf16 v[100:103], v[174:177], v[198:201], v[100:103]
	v_mfma_f32_16x16x32_bf16 v[96:99], v[182:185], v[198:201], v[96:99]
	v_mfma_f32_16x16x32_bf16 v[84:87], v[174:177], v[206:209], v[84:87]
	v_mfma_f32_16x16x32_bf16 v[80:83], v[182:185], v[206:209], v[80:83]
	v_mfma_f32_16x16x32_bf16 v[68:71], v[174:177], v[214:217], v[68:71]
	v_mfma_f32_16x16x32_bf16 v[64:67], v[182:185], v[214:217], v[64:67]
	s_setprio 0
	s_barrier
	s_add_i32 s33, s52, s36
	v_lshl_add_u64 v[218:219], s[24:25], 0, v[132:133]
	s_mov_b32 m0, s33
	ds_read_b128 v[186:189], v153 offset:16384
	ds_read_b128 v[190:193], v153 offset:17408
	ds_read_b128 v[194:197], v153 offset:18432
	ds_read_b128 v[198:201], v153 offset:19456
	ds_read_b128 v[202:205], v153 offset:20480
	ds_read_b128 v[206:209], v153 offset:21504
	ds_read_b128 v[210:213], v153 offset:22528
	ds_read_b128 v[214:217], v153 offset:23552
	global_load_lds_dwordx4 v[218:219], off
	s_add_i32 m0, s33, 0x2000
	s_add_u32 s62, s24, 0x40000
	v_lshl_add_u64 v[220:221], s[24:25], 0, v[128:129]
	s_addc_u32 s63, s25, 0
	s_add_i32 s33, s53, s36
	global_load_lds_dwordx4 v[220:221], off
	v_lshl_add_u64 v[222:223], s[62:63], 0, v[132:133]
	s_mov_b32 m0, s33
	v_lshl_add_u64 v[224:225], s[26:27], 0, v[130:131]
	global_load_lds_dwordx4 v[222:223], off
	v_lshl_add_u64 v[222:223], s[62:63], 0, v[128:129]
	s_add_i32 m0, s33, 0x2000
	s_nop 0
	global_load_lds_dwordx4 v[222:223], off
	v_lshl_add_u64 v[222:223], s[26:27], 0, v[134:135]
	s_mov_b32 m0, s39
	s_nop 0
	global_load_lds_dwordx4 v[222:223], off
	s_mov_b32 m0, s40
	s_nop 0
	global_load_lds_dwordx4 v[224:225], off
	s_waitcnt vmcnt(8)
	s_waitcnt lgkmcnt(0)
	s_barrier
; #define PG8_STAGE(bufoff, gbase, voff) do { _Pragma("unroll") for (int _i = 0; _i < 2; ++_i) \
;         __builtin_amdgcn_global_load_lds((const unsigned*)((const char*)(gbase) + (voff)[_i]), (LAS unsigned*)(lds + (bufoff) + ldsw + _i * 8192), 16, 0, 0); } while (0)
; #define PG8_LDA(dst, b, h) do { _Pragma("unroll") for (int m = 0; m < 4; ++m) _Pragma("unroll") for (int k = 0; k < 2; ++k) dst[m][k] = *(const LAS bf16x8*)(lds + PG8_SA(b, h) + aoff + m * 2048 + k * 1024); } while (0)
; #define PG8_LDB(dst, b, h) do { _Pragma("unroll") for (int n = 0; n < 2; ++n) _Pragma("unroll") for (int k = 0; k < 2; ++k) dst[n][k] = *(const LAS bf16x8*)(lds + PG8_SB(b, h) + boff + n * 2048 + k * 1024); } while (0)
; #define PG8_MMA(ai, bj, At, Bt) do { __builtin_amdgcn_s_setprio(1); _Pragma("unroll") for (int m = 0; m < 4; ++m) _Pragma("unroll") for (int n = 0; n < 2; ++n) _Pragma("unroll") for (int k = 0; k < 2; ++k) \
;         acc[ai][bj][m][n] = __builtin_amdgcn_mfma_f32_16x16x32_bf16(Bt[n][k], At[m][k], acc[ai][bj][m][n], 0, 0, 0); __builtin_amdgcn_s_setprio(0); } while (0)
; #define PG8_WAIT_V(n) asm volatile("s_waitcnt vmcnt(" #n ")" ::: "memory")
; #define PG8_WAIT_L(n) asm volatile("s_waitcnt lgkmcnt(" #n ")" ::: "memory")
; #define PG8_BAR __builtin_amdgcn_s_barrier()
; #define PG8_SCHED __builtin_amdgcn_sched_barrier(0)
; template <class Epi>
; __device__ __forceinline__ void gemm_phase(LAS unsigned char* lds, const Gemm g, const StaticOrder& S, const Epi& E) {
;     ...
;             PG8_WAIT_V(8); PG8_WAIT_L(0); PG8_BAR; PG8_MMA(1, 0, At, B0); PG8_MMA(1, 1, At, B1); PG8_BAR; PG8_SCHED;
;             PG8_LDB(B0, 1, 0); PG8_LDB(B1, 1, 1); PG8_SCHED; PG8_LDA(At, 1, 0); PG8_STAGE(PG8_SA(0, 1), a2 + hsA, voffA);
;             PG8_WAIT_V(8); PG8_WAIT_L(0); PG8_BAR; PG8_MMA(0, 0, At, B0); PG8_MMA(0, 1, At, B1); PG8_BAR; PG8_SCHED;
	s_setprio 1
	s_waitcnt lgkmcnt(0)
	v_mfma_f32_16x16x32_bf16 v[60:63], v[144:147], v[186:189], 0
	v_mfma_f32_16x16x32_bf16 v[56:59], v[162:165], v[186:189], 0
	v_mfma_f32_16x16x32_bf16 v[44:47], v[144:147], v[194:197], 0
	v_mfma_f32_16x16x32_bf16 v[40:43], v[162:165], v[194:197], 0
	v_mfma_f32_16x16x32_bf16 v[28:31], v[144:147], v[202:205], 0
	v_mfma_f32_16x16x32_bf16 v[24:27], v[162:165], v[202:205], 0
	v_mfma_f32_16x16x32_bf16 v[12:15], v[144:147], v[210:213], 0
	v_mfma_f32_16x16x32_bf16 v[8:11], v[162:165], v[210:213], 0
	v_mfma_f32_16x16x32_bf16 v[60:63], v[158:161], v[190:193], v[60:63]
	v_mfma_f32_16x16x32_bf16 v[56:59], v[166:169], v[190:193], v[56:59]
	v_mfma_f32_16x16x32_bf16 v[44:47], v[158:161], v[198:201], v[44:47]
	v_mfma_f32_16x16x32_bf16 v[40:43], v[166:169], v[198:201], v[40:43]
	v_mfma_f32_16x16x32_bf16 v[28:31], v[158:161], v[206:209], v[28:31]
	v_mfma_f32_16x16x32_bf16 v[24:27], v[166:169], v[206:209], v[24:27]
	v_mfma_f32_16x16x32_bf16 v[12:15], v[158:161], v[214:217], v[12:15]
	v_mfma_f32_16x16x32_bf16 v[8:11], v[166:169], v[214:217], v[8:11]
	s_setprio 0
	s_setprio 1
	v_mfma_f32_16x16x32_bf16 v[52:55], v[170:173], v[186:189], 0
	v_mfma_f32_16x16x32_bf16 v[48:51], v[178:181], v[186:189], 0
	v_mfma_f32_16x16x32_bf16 v[36:39], v[170:173], v[194:197], 0
	v_mfma_f32_16x16x32_bf16 v[32:35], v[178:181], v[194:197], 0
	v_mfma_f32_16x16x32_bf16 v[20:23], v[170:173], v[202:205], 0
	v_mfma_f32_16x16x32_bf16 v[16:19], v[178:181], v[202:205], 0
	v_mfma_f32_16x16x32_bf16 v[4:7], v[170:173], v[210:213], 0
	v_mfma_f32_16x16x32_bf16 v[0:3], v[178:181], v[210:213], 0
	v_mfma_f32_16x16x32_bf16 v[52:55], v[174:177], v[190:193], v[52:55]
	v_mfma_f32_16x16x32_bf16 v[48:51], v[182:185], v[190:193], v[48:51]
	v_mfma_f32_16x16x32_bf16 v[36:39], v[174:177], v[198:201], v[36:39]
	v_mfma_f32_16x16x32_bf16 v[32:35], v[182:185], v[198:201], v[32:35]
	v_mfma_f32_16x16x32_bf16 v[20:23], v[174:177], v[206:209], v[20:23]
	v_mfma_f32_16x16x32_bf16 v[16:19], v[182:185], v[206:209], v[16:19]
	v_mfma_f32_16x16x32_bf16 v[4:7], v[174:177], v[214:217], v[4:7]
	v_mfma_f32_16x16x32_bf16 v[0:3], v[182:185], v[214:217], v[0:3]
	s_setprio 0
	s_barrier
	s_add_i32 s33, 0, 0x18000
	v_add_u32_e32 v155, s33, v149
	s_add_i32 s61, 0, 0x1c000
	ds_read_b128 v[144:147], v155
	ds_read_b128 v[158:161], v155 offset:1024
	ds_read_b128 v[162:165], v155 offset:2048
	ds_read_b128 v[166:169], v155 offset:3072
	v_add_u32_e32 v155, s61, v149
	ds_read_b128 v[170:173], v155
	ds_read_b128 v[174:177], v155 offset:1024
	ds_read_b128 v[178:181], v155 offset:2048
	ds_read_b128 v[182:185], v155 offset:3072
	s_add_u32 s26, s26, 0x40000
	s_addc_u32 s27, s27, 0
	s_mov_b32 m0, s41
	v_lshl_add_u64 v[226:227], s[26:27], 0, v[134:135]
	ds_read_b128 v[186:189], v153 offset:32768
	ds_read_b128 v[190:193], v153 offset:33792
	ds_read_b128 v[194:197], v153 offset:34816
	ds_read_b128 v[198:201], v153 offset:35840
	ds_read_b128 v[202:205], v153 offset:36864
	ds_read_b128 v[206:209], v153 offset:37888
	ds_read_b128 v[210:213], v153 offset:38912
	ds_read_b128 v[214:217], v153 offset:39936
	global_load_lds_dwordx4 v[226:227], off
	v_lshl_add_u64 v[226:227], s[26:27], 0, v[130:131]
	s_mov_b32 m0, s42
	s_nop 0
	global_load_lds_dwordx4 v[226:227], off
	s_waitcnt vmcnt(8)
	s_waitcnt lgkmcnt(0)
	s_barrier
	s_setprio 1
	s_waitcnt lgkmcnt(0)
	v_mfma_f32_16x16x32_bf16 v[124:127], v[144:147], v[186:189], v[124:127]
	v_mfma_f32_16x16x32_bf16 v[120:123], v[162:165], v[186:189], v[120:123]
	v_mfma_f32_16x16x32_bf16 v[108:111], v[144:147], v[194:197], v[108:111]
	v_mfma_f32_16x16x32_bf16 v[104:107], v[162:165], v[194:197], v[104:107]
	v_mfma_f32_16x16x32_bf16 v[92:95], v[144:147], v[202:205], v[92:95]
	v_mfma_f32_16x16x32_bf16 v[88:91], v[162:165], v[202:205], v[88:91]
	v_mfma_f32_16x16x32_bf16 v[76:79], v[144:147], v[210:213], v[76:79]
	v_mfma_f32_16x16x32_bf16 v[72:75], v[162:165], v[210:213], v[72:75]
	v_mfma_f32_16x16x32_bf16 v[124:127], v[158:161], v[190:193], v[124:127]
	v_mfma_f32_16x16x32_bf16 v[120:123], v[166:169], v[190:193], v[120:123]
	v_mfma_f32_16x16x32_bf16 v[108:111], v[158:161], v[198:201], v[108:111]
	v_mfma_f32_16x16x32_bf16 v[104:107], v[166:169], v[198:201], v[104:107]
	v_mfma_f32_16x16x32_bf16 v[92:95], v[158:161], v[206:209], v[92:95]
	v_mfma_f32_16x16x32_bf16 v[88:91], v[166:169], v[206:209], v[88:91]
	v_mfma_f32_16x16x32_bf16 v[76:79], v[158:161], v[214:217], v[76:79]
	v_mfma_f32_16x16x32_bf16 v[72:75], v[166:169], v[214:217], v[72:75]
	s_setprio 0
	s_setprio 1
	v_mfma_f32_16x16x32_bf16 v[116:119], v[170:173], v[186:189], v[116:119]
	v_mfma_f32_16x16x32_bf16 v[112:115], v[178:181], v[186:189], v[112:115]
	v_mfma_f32_16x16x32_bf16 v[100:103], v[170:173], v[194:197], v[100:103]
	v_mfma_f32_16x16x32_bf16 v[96:99], v[178:181], v[194:197], v[96:99]
	v_mfma_f32_16x16x32_bf16 v[84:87], v[170:173], v[202:205], v[84:87]
	v_mfma_f32_16x16x32_bf16 v[80:83], v[178:181], v[202:205], v[80:83]
	v_mfma_f32_16x16x32_bf16 v[68:71], v[170:173], v[210:213], v[68:71]
	v_mfma_f32_16x16x32_bf16 v[64:67], v[178:181], v[210:213], v[64:67]
	v_mfma_f32_16x16x32_bf16 v[116:119], v[174:177], v[190:193], v[116:119]
	v_mfma_f32_16x16x32_bf16 v[112:115], v[182:185], v[190:193], v[112:115]
	v_mfma_f32_16x16x32_bf16 v[100:103], v[174:177], v[198:201], v[100:103]
	v_mfma_f32_16x16x32_bf16 v[96:99], v[182:185], v[198:201], v[96:99]
	v_mfma_f32_16x16x32_bf16 v[84:87], v[174:177], v[206:209], v[84:87]
	v_mfma_f32_16x16x32_bf16 v[80:83], v[182:185], v[206:209], v[80:83]
	v_mfma_f32_16x16x32_bf16 v[68:71], v[174:177], v[214:217], v[68:71]
	v_mfma_f32_16x16x32_bf16 v[64:67], v[182:185], v[214:217], v[64:67]
	s_setprio 0
	s_barrier
; #define PG8_STAGE(bufoff, gbase, voff) do { _Pragma("unroll") for (int _i = 0; _i < 2; ++_i) \
;         __builtin_amdgcn_global_load_lds((const unsigned*)((const char*)(gbase) + (voff)[_i]), (LAS unsigned*)(lds + (bufoff) + ldsw + _i * 8192), 16, 0, 0); } while (0)
; #define PG8_LDA(dst, b, h) do { _Pragma("unroll") for (int m = 0; m < 4; ++m) _Pragma("unroll") for (int k = 0; k < 2; ++k) dst[m][k] = *(const LAS bf16x8*)(lds + PG8_SA(b, h) + aoff + m * 2048 + k * 1024); } while (0)
; #define PG8_MMA(ai, bj, At, Bt) do { __builtin_amdgcn_s_setprio(1); _Pragma("unroll") for (int m = 0; m < 4; ++m) _Pragma("unroll") for (int n = 0; n < 2; ++n) _Pragma("unroll") for (int k = 0; k < 2; ++k) \
;         acc[ai][bj][m][n] = __builtin_amdgcn_mfma_f32_16x16x32_bf16(Bt[n][k], At[m][k], acc[ai][bj][m][n], 0, 0, 0); __builtin_amdgcn_s_setprio(0); } while (0)
; #define PG8_WAIT_V(n) asm volatile("s_waitcnt vmcnt(" #n ")" ::: "memory")
; #define PG8_WAIT_L(n) asm volatile("s_waitcnt lgkmcnt(" #n ")" ::: "memory")
; #define PG8_BAR __builtin_amdgcn_s_barrier()
; #define PG8_SCHED __builtin_amdgcn_sched_barrier(0)
; template <class Epi>
; __device__ __forceinline__ void gemm_phase(LAS unsigned char* lds, const Gemm g, const StaticOrder& S, const Epi& E) {
;     ...
;         for (int t = 0; t < nt; t += 2) {
;     ...
;             PG8_LDA(At, 1, 1); PG8_STAGE(PG8_SB(1, 0), b3, voffB); PG8_STAGE(PG8_SB(1, 1), b3 + hsB, voffB); PG8_STAGE(PG8_SA(1, 0), a3, voffA);
;             PG8_WAIT_V(8); PG8_WAIT_L(0); PG8_BAR; PG8_MMA(1, 0, At, B0); PG8_MMA(1, 1, At, B1); PG8_BAR; PG8_SCHED;
	s_add_i32 s26, s33, s36
	v_lshl_add_u64 v[218:219], v[218:219], 0, s[10:11]
	s_mov_b32 m0, s26
	ds_read_b128 v[186:189], v153 offset:49152
	ds_read_b128 v[190:193], v153 offset:50176
	ds_read_b128 v[194:197], v153 offset:51200
	ds_read_b128 v[198:201], v153 offset:52224
	ds_read_b128 v[202:205], v153 offset:53248
	ds_read_b128 v[206:209], v153 offset:54272
	ds_read_b128 v[210:213], v153 offset:55296
	ds_read_b128 v[214:217], v153 offset:56320
	global_load_lds_dwordx4 v[218:219], off
	s_add_i32 m0, s26, 0x2000
	s_add_u32 s24, s24, 0x40080
	v_lshl_add_u64 v[218:219], v[220:221], 0, s[10:11]
	s_addc_u32 s25, s25, 0
	s_add_i32 s26, s61, s36
	global_load_lds_dwordx4 v[218:219], off
	v_lshl_add_u64 v[218:219], s[24:25], 0, v[132:133]
	s_mov_b32 m0, s26
	s_nop 0
	global_load_lds_dwordx4 v[218:219], off
	v_lshl_add_u64 v[218:219], s[24:25], 0, v[128:129]
	s_add_i32 m0, s26, 0x2000
	s_nop 0
	global_load_lds_dwordx4 v[218:219], off
	v_lshl_add_u64 v[218:219], v[222:223], 0, s[10:11]
	s_mov_b32 m0, s48
	s_nop 0
	global_load_lds_dwordx4 v[218:219], off
	v_lshl_add_u64 v[218:219], v[224:225], 0, s[10:11]
	s_mov_b32 m0, s49
	s_nop 0
	global_load_lds_dwordx4 v[218:219], off
	s_waitcnt vmcnt(8)
	s_waitcnt lgkmcnt(0)
	s_barrier
	s_setprio 1
	s_waitcnt lgkmcnt(0)
	v_mfma_f32_16x16x32_bf16 v[60:63], v[144:147], v[186:189], v[60:63]
	v_mfma_f32_16x16x32_bf16 v[56:59], v[162:165], v[186:189], v[56:59]
	v_mfma_f32_16x16x32_bf16 v[44:47], v[144:147], v[194:197], v[44:47]
	v_mfma_f32_16x16x32_bf16 v[40:43], v[162:165], v[194:197], v[40:43]
	v_mfma_f32_16x16x32_bf16 v[28:31], v[144:147], v[202:205], v[28:31]
	v_mfma_f32_16x16x32_bf16 v[24:27], v[162:165], v[202:205], v[24:27]
	v_mfma_f32_16x16x32_bf16 v[12:15], v[144:147], v[210:213], v[12:15]
	v_mfma_f32_16x16x32_bf16 v[8:11], v[162:165], v[210:213], v[8:11]
	v_mfma_f32_16x16x32_bf16 v[60:63], v[158:161], v[190:193], v[60:63]
	v_mfma_f32_16x16x32_bf16 v[56:59], v[166:169], v[190:193], v[56:59]
	v_mfma_f32_16x16x32_bf16 v[44:47], v[158:161], v[198:201], v[44:47]
	v_mfma_f32_16x16x32_bf16 v[40:43], v[166:169], v[198:201], v[40:43]
	v_mfma_f32_16x16x32_bf16 v[28:31], v[158:161], v[206:209], v[28:31]
	v_mfma_f32_16x16x32_bf16 v[24:27], v[166:169], v[206:209], v[24:27]
	v_mfma_f32_16x16x32_bf16 v[12:15], v[158:161], v[214:217], v[12:15]
	v_mfma_f32_16x16x32_bf16 v[8:11], v[166:169], v[214:217], v[8:11]
	s_setprio 0
	s_setprio 1
	v_mfma_f32_16x16x32_bf16 v[52:55], v[170:173], v[186:189], v[52:55]
	v_mfma_f32_16x16x32_bf16 v[48:51], v[178:181], v[186:189], v[48:51]
	v_mfma_f32_16x16x32_bf16 v[36:39], v[170:173], v[194:197], v[36:39]
	v_mfma_f32_16x16x32_bf16 v[32:35], v[178:181], v[194:197], v[32:35]
	v_mfma_f32_16x16x32_bf16 v[20:23], v[170:173], v[202:205], v[20:23]
	v_mfma_f32_16x16x32_bf16 v[16:19], v[178:181], v[202:205], v[16:19]
	v_mfma_f32_16x16x32_bf16 v[4:7], v[170:173], v[210:213], v[4:7]
	v_mfma_f32_16x16x32_bf16 v[0:3], v[178:181], v[210:213], v[0:3]
	v_mfma_f32_16x16x32_bf16 v[52:55], v[174:177], v[190:193], v[52:55]
	v_mfma_f32_16x16x32_bf16 v[48:51], v[182:185], v[190:193], v[48:51]
	v_mfma_f32_16x16x32_bf16 v[36:39], v[174:177], v[198:201], v[36:39]
	v_mfma_f32_16x16x32_bf16 v[32:35], v[182:185], v[198:201], v[32:35]
	v_mfma_f32_16x16x32_bf16 v[20:23], v[174:177], v[206:209], v[20:23]
	v_mfma_f32_16x16x32_bf16 v[16:19], v[182:185], v[206:209], v[16:19]
	v_mfma_f32_16x16x32_bf16 v[4:7], v[174:177], v[214:217], v[4:7]
	v_mfma_f32_16x16x32_bf16 v[0:3], v[182:185], v[214:217], v[0:3]
	s_setprio 0
	s_barrier
	s_add_i32 s60, s60, 2
	s_add_u32 s22, s22, 0x100
	s_addc_u32 s23, s23, 0
	s_add_u32 s58, s58, 0x100
	s_addc_u32 s59, s59, 0
	s_cmp_gt_u32 s60, 13
	s_cbranch_scc0 .LBB0_1558
	s_branch .Lpeel_exit7

; __device__ __forceinline__ float sigmoidf_(float x) { return __builtin_amdgcn_rcpf(1.f + __expf(-x)); }
;     __device__ __forceinline__ void operator()(const AccT& acc, const Unit& u, int wr, int wc, int fr, int fq) const {
;         const int row0 = u.pm * BM + wr * 64 + fr, col = u.pn * 128 + wc * 32 + 8 * fq;
; #pragma unroll
;         for (int ai = 0; ai < 2; ++ai)
; #pragma unroll
;             for (int m = 0; m < 4; ++m) {
;                 const int row = row0 + ai * HALF + m * 16;
;                 const float rs = rsqrtf(ss[row] * (1.f / 1024.f) + EPS);
;                 float o[8];
; #pragma unroll
;                 for (int n = 0; n < 2; ++n)
; #pragma unroll
;                     for (int j = 0; j < 4; ++j) { const float gt = acc[ai][0][m][n][j] * rs, up = acc[ai][1][m][n][j] * rs; o[n * 4 + j] = gt * up * sigmoidf_(gt); }
;                 *(u32x4*)(O + (size_t)row * FF + col) = pack8(o);
.LBB0_1561:
	v_lshl_add_u32 v144, s0, 8, v148
	v_ashrrev_i32_e32 v145, 31, v144
	v_lshl_add_u64 v[146:147], v[144:145], 2, s[8:9]
	v_mov_b32_e32 v163, v114
	v_mov_b32_e32 v114, v123
	v_mov_b32_e32 v160, v124
	v_mov_b32_e32 v161, v116
	v_mov_b32_e32 v116, v125
	v_mov_b32_e32 v124, v126
	v_mov_b32_e32 v125, v118
	v_mov_b32_e32 v118, v127
	v_mov_b32_e32 v126, v120
	v_mov_b32_e32 v127, v112
	v_mov_b32_e32 v112, v121
	v_mov_b32_e32 v162, v122
	v_lshl_or_b32 v158, s1, 7, v150
	v_mov_b64_e32 v[120:121], s[44:45]
	v_ashrrev_i32_e32 v159, 31, v158
	v_mad_i64_i32 v[164:165], s[0:1], v144, s55, v[120:121]
	v_or_b32_e32 v166, 16, v144
	v_lshlrev_b64 v[122:123], 1, v[158:159]
	v_ashrrev_i32_e32 v167, 31, v166
	v_lshl_add_u64 v[158:159], v[164:165], 0, v[122:123]
	v_lshl_add_u64 v[164:165], v[166:167], 2, s[8:9]
	s_nop 0
	v_fmamk_f32 v145, v232, 0x3a800000, v154
	v_mul_f32_e32 v155, 0x4b800000, v145
	v_cmp_gt_f32_e32 vcc, s54, v145
	s_nop 1
	v_cndmask_b32_e32 v145, v145, v155, vcc
	v_rsq_f32_e32 v145, v145
	s_nop 0
	v_mul_f32_e32 v155, 0x45800000, v145
	v_cndmask_b32_e32 v168, v145, v155, vcc
	v_pk_mul_f32 v[114:115], v[114:115], v[168:169] op_sel_hi:[1,0]
	v_pk_mul_f32 v[160:161], v[160:161], v[168:169] op_sel_hi:[1,0]
	v_pk_mul_f32 v[116:117], v[116:117], v[168:169] op_sel_hi:[1,0]
	v_pk_mul_f32 v[124:125], v[124:125], v[168:169] op_sel_hi:[1,0]
	v_pk_mul_f32 v[118:119], v[118:119], v[168:169] op_sel_hi:[1,0]
	v_pk_mul_f32 v[126:127], v[126:127], v[168:169] op_sel_hi:[1,0]
	v_pk_mul_f32 v[112:113], v[112:113], v[168:169] op_sel_hi:[1,0]
	v_pk_mul_f32 v[162:163], v[162:163], v[168:169] op_sel_hi:[1,0]
	v_mul_f32_e32 v115, v114, v115
	v_mul_f32_e32 v114, 0xbfb8aa3b, v114
	v_mul_f32_e32 v145, v160, v161
	v_mul_f32_e32 v155, 0xbfb8aa3b, v160
	v_mul_f32_e32 v117, v116, v117
	v_mul_f32_e32 v116, 0xbfb8aa3b, v116
	v_mul_f32_e32 v125, v124, v125
	v_mul_f32_e32 v124, 0xbfb8aa3b, v124
	v_mul_f32_e32 v119, v118, v119
	v_mul_f32_e32 v118, 0xbfb8aa3b, v118
	v_mul_f32_e32 v127, v126, v127
	v_mul_f32_e32 v126, 0xbfb8aa3b, v126
	v_mul_f32_e32 v113, v112, v113
	v_mul_f32_e32 v112, 0xbfb8aa3b, v112
	v_mul_f32_e32 v160, 0xbfb8aa3b, v162
	v_exp_f32_e32 v114, v114
	v_exp_f32_e32 v155, v155
	v_exp_f32_e32 v116, v116
	v_exp_f32_e32 v124, v124
	v_exp_f32_e32 v118, v118
	v_exp_f32_e32 v126, v126
	v_exp_f32_e32 v112, v112
	v_exp_f32_e32 v160, v160
	v_add_f32_e32 v114, 1.0, v114
	v_add_f32_e32 v155, 1.0, v155
	v_add_f32_e32 v116, 1.0, v116
	v_add_f32_e32 v124, 1.0, v124
	v_add_f32_e32 v118, 1.0, v118
	v_add_f32_e32 v126, 1.0, v126
	v_add_f32_e32 v112, 1.0, v112
	v_add_f32_e32 v160, 1.0, v160
	v_rcp_f32_e32 v114, v114
	v_rcp_f32_e32 v155, v155
	v_rcp_f32_e32 v116, v116
	v_rcp_f32_e32 v124, v124
	v_rcp_f32_e32 v118, v118
	v_rcp_f32_e32 v126, v126
	v_rcp_f32_e32 v112, v112
	v_rcp_f32_e32 v160, v160
	v_mul_f32_e32 v157, v162, v163
	v_mul_f32_e32 v115, v115, v114
	v_mul_f32_e32 v145, v145, v155
	v_mul_f32_e32 v116, v117, v116
	v_mul_f32_e32 v117, v125, v124
	v_mul_f32_e32 v118, v119, v118
	v_mul_f32_e32 v119, v127, v126
	v_mul_f32_e32 v124, v113, v112
	v_mul_f32_e32 v125, v157, v160
	v_cvt_pk_bf16_f32 v112, v145, v116
	v_cvt_pk_bf16_f32 v113, v117, v118
	v_cvt_pk_bf16_f32 v114, v119, v124
	v_cvt_pk_bf16_f32 v115, v125, v115
	global_store_dwordx4 v[158:159], v[112:115], off
	s_nop 0
	s_nop 0
	v_mov_b32_e32 v113, v100
	v_mov_b32_e32 v100, v109
	v_mov_b32_e32 v109, v102
	v_mov_b32_e32 v102, v111
	v_mov_b32_e32 v111, v96
	v_mov_b32_e32 v96, v105
	v_mov_b32_e32 v105, v98
	v_mov_b32_e32 v98, v107
	v_mov_b32_e32 v112, v108
	v_mov_b32_e32 v108, v110
	v_mov_b32_e32 v110, v104
	v_mov_b32_e32 v104, v106
	v_or_b32_e32 v106, 32, v144
	v_mad_i64_i32 v[114:115], s[0:1], v166, s55, v[120:121]
	v_lshl_add_u64 v[114:115], v[114:115], 0, v[122:123]
	s_nop 0
	v_fmamk_f32 v107, v233, 0x3a800000, v154
	v_mul_f32_e32 v116, 0x4b800000, v107
	v_cmp_gt_f32_e32 vcc, s54, v107
	s_nop 1
	v_cndmask_b32_e32 v107, v107, v116, vcc
	v_rsq_f32_e32 v118, v107
	v_ashrrev_i32_e32 v107, 31, v106
	v_lshl_add_u64 v[116:117], v[106:107], 2, s[8:9]
	v_mul_f32_e32 v107, 0x45800000, v118
	v_cndmask_b32_e32 v118, v118, v107, vcc
	v_pk_mul_f32 v[98:99], v[98:99], v[118:119] op_sel_hi:[1,0]
	v_pk_mul_f32 v[112:113], v[112:113], v[118:119] op_sel_hi:[1,0]
	v_pk_mul_f32 v[100:101], v[100:101], v[118:119] op_sel_hi:[1,0]
	v_pk_mul_f32 v[108:109], v[108:109], v[118:119] op_sel_hi:[1,0]
	v_pk_mul_f32 v[102:103], v[102:103], v[118:119] op_sel_hi:[1,0]
	v_pk_mul_f32 v[110:111], v[110:111], v[118:119] op_sel_hi:[1,0]
	v_pk_mul_f32 v[96:97], v[96:97], v[118:119] op_sel_hi:[1,0]
	v_pk_mul_f32 v[104:105], v[104:105], v[118:119] op_sel_hi:[1,0]
	v_mul_f32_e32 v99, v98, v99
	v_mul_f32_e32 v98, 0xbfb8aa3b, v98
	v_mul_f32_e32 v107, v112, v113
	v_mul_f32_e32 v112, 0xbfb8aa3b, v112
	v_mul_f32_e32 v101, v100, v101
	v_mul_f32_e32 v100, 0xbfb8aa3b, v100
	v_mul_f32_e32 v109, v108, v109
	v_mul_f32_e32 v108, 0xbfb8aa3b, v108
	v_mul_f32_e32 v103, v102, v103
	v_mul_f32_e32 v102, 0xbfb8aa3b, v102
	v_mul_f32_e32 v111, v110, v111
	v_mul_f32_e32 v110, 0xbfb8aa3b, v110
	v_mul_f32_e32 v97, v96, v97
	v_mul_f32_e32 v96, 0xbfb8aa3b, v96
	v_mul_f32_e32 v105, v104, v105
	v_mul_f32_e32 v104, 0xbfb8aa3b, v104
	v_exp_f32_e32 v98, v98
	v_exp_f32_e32 v112, v112
	v_exp_f32_e32 v100, v100
	v_exp_f32_e32 v108, v108
	v_exp_f32_e32 v102, v102
	v_exp_f32_e32 v110, v110
	v_exp_f32_e32 v96, v96
	v_exp_f32_e32 v104, v104
	v_add_f32_e32 v98, 1.0, v98
	v_add_f32_e32 v112, 1.0, v112
	v_add_f32_e32 v100, 1.0, v100
	v_add_f32_e32 v108, 1.0, v108
	v_add_f32_e32 v102, 1.0, v102
	v_add_f32_e32 v110, 1.0, v110
	v_add_f32_e32 v96, 1.0, v96
	v_add_f32_e32 v104, 1.0, v104
	v_rcp_f32_e32 v98, v98
; __device__ __forceinline__ float sigmoidf_(float x) { return __builtin_amdgcn_rcpf(1.f + __expf(-x)); }
;     __device__ __forceinline__ void operator()(const AccT& acc, const Unit& u, int wr, int wc, int fr, int fq) const {
;     ...
;             for (int m = 0; m < 4; ++m) {
;                 const int row = row0 + ai * HALF + m * 16;
;                 const float rs = rsqrtf(ss[row] * (1.f / 1024.f) + EPS);
;                 float o[8];
; #pragma unroll
;                 for (int n = 0; n < 2; ++n)
; #pragma unroll
;                     for (int j = 0; j < 4; ++j) { const float gt = acc[ai][0][m][n][j] * rs, up = acc[ai][1][m][n][j] * rs; o[n * 4 + j] = gt * up * sigmoidf_(gt); }
;                 *(u32x4*)(O + (size_t)row * FF + col) = pack8(o);
	v_rcp_f32_e32 v112, v112
	v_rcp_f32_e32 v100, v100
	v_rcp_f32_e32 v108, v108
	v_rcp_f32_e32 v102, v102
	v_rcp_f32_e32 v110, v110
	v_rcp_f32_e32 v96, v96
	v_rcp_f32_e32 v104, v104
	v_mul_f32_e32 v99, v99, v98
	v_mul_f32_e32 v107, v107, v112
	v_mul_f32_e32 v100, v101, v100
	v_mul_f32_e32 v101, v109, v108
	v_mul_f32_e32 v102, v103, v102
	v_mul_f32_e32 v103, v111, v110
	v_mul_f32_e32 v108, v97, v96
	v_mul_f32_e32 v104, v105, v104
	v_cvt_pk_bf16_f32 v96, v107, v100
	v_cvt_pk_bf16_f32 v97, v101, v102
	v_cvt_pk_bf16_f32 v98, v103, v108
	v_cvt_pk_bf16_f32 v99, v104, v99
	global_store_dwordx4 v[114:115], v[96:99], off
	s_nop 0
	s_nop 0
	v_mov_b32_e32 v97, v84
	v_mov_b32_e32 v84, v93
	v_mov_b32_e32 v93, v86
	v_mov_b32_e32 v86, v95
	v_mov_b32_e32 v95, v80
	v_mov_b32_e32 v80, v89
	v_mov_b32_e32 v89, v82
	v_mov_b32_e32 v82, v91
	v_mov_b32_e32 v96, v92
	v_mov_b32_e32 v92, v94
	v_mov_b32_e32 v94, v88
	v_mov_b32_e32 v88, v90
	v_or_b32_e32 v90, 48, v144
	v_mad_i64_i32 v[98:99], s[0:1], v106, s55, v[120:121]
	v_lshl_add_u64 v[98:99], v[98:99], 0, v[122:123]
	s_nop 0
	v_fmamk_f32 v91, v234, 0x3a800000, v154
	v_mul_f32_e32 v100, 0x4b800000, v91
	v_cmp_gt_f32_e32 vcc, s54, v91
	s_nop 1
	v_cndmask_b32_e32 v91, v91, v100, vcc
	v_rsq_f32_e32 v102, v91
	v_ashrrev_i32_e32 v91, 31, v90
	v_lshl_add_u64 v[100:101], v[90:91], 2, s[8:9]
	v_mul_f32_e32 v91, 0x45800000, v102
	v_cndmask_b32_e32 v102, v102, v91, vcc
	v_pk_mul_f32 v[82:83], v[82:83], v[102:103] op_sel_hi:[1,0]
	v_pk_mul_f32 v[96:97], v[96:97], v[102:103] op_sel_hi:[1,0]
	v_pk_mul_f32 v[84:85], v[84:85], v[102:103] op_sel_hi:[1,0]
	v_pk_mul_f32 v[92:93], v[92:93], v[102:103] op_sel_hi:[1,0]
	v_pk_mul_f32 v[86:87], v[86:87], v[102:103] op_sel_hi:[1,0]
	v_pk_mul_f32 v[94:95], v[94:95], v[102:103] op_sel_hi:[1,0]
	v_pk_mul_f32 v[80:81], v[80:81], v[102:103] op_sel_hi:[1,0]
	v_pk_mul_f32 v[88:89], v[88:89], v[102:103] op_sel_hi:[1,0]
	v_mul_f32_e32 v83, v82, v83
	v_mul_f32_e32 v82, 0xbfb8aa3b, v82
	v_mul_f32_e32 v91, v96, v97
	v_mul_f32_e32 v96, 0xbfb8aa3b, v96
	v_mul_f32_e32 v85, v84, v85
	v_mul_f32_e32 v84, 0xbfb8aa3b, v84
	v_mul_f32_e32 v93, v92, v93
	v_mul_f32_e32 v92, 0xbfb8aa3b, v92
	v_mul_f32_e32 v87, v86, v87
	v_mul_f32_e32 v86, 0xbfb8aa3b, v86
	v_mul_f32_e32 v95, v94, v95
	v_mul_f32_e32 v94, 0xbfb8aa3b, v94
	v_mul_f32_e32 v81, v80, v81
	v_mul_f32_e32 v80, 0xbfb8aa3b, v80
	v_mul_f32_e32 v89, v88, v89
	v_mul_f32_e32 v88, 0xbfb8aa3b, v88
	v_exp_f32_e32 v82, v82
	v_exp_f32_e32 v96, v96
	v_exp_f32_e32 v84, v84
	v_exp_f32_e32 v92, v92
	v_exp_f32_e32 v86, v86
	v_exp_f32_e32 v94, v94
	v_exp_f32_e32 v80, v80
	v_exp_f32_e32 v88, v88
	v_add_f32_e32 v82, 1.0, v82
	v_add_f32_e32 v96, 1.0, v96
	v_add_f32_e32 v84, 1.0, v84
	v_add_f32_e32 v92, 1.0, v92
	v_add_f32_e32 v86, 1.0, v86
	v_add_f32_e32 v94, 1.0, v94
	v_add_f32_e32 v80, 1.0, v80
	v_add_f32_e32 v88, 1.0, v88
	v_rcp_f32_e32 v82, v82
	v_rcp_f32_e32 v96, v96
	v_rcp_f32_e32 v84, v84
	v_rcp_f32_e32 v92, v92
	v_rcp_f32_e32 v86, v86
	v_rcp_f32_e32 v94, v94
	v_rcp_f32_e32 v80, v80
	v_rcp_f32_e32 v88, v88
	v_mul_f32_e32 v83, v83, v82
	v_mul_f32_e32 v91, v91, v96
	v_mul_f32_e32 v84, v85, v84
	v_mul_f32_e32 v85, v93, v92
	v_mul_f32_e32 v86, v87, v86
	v_mul_f32_e32 v87, v95, v94
	v_mul_f32_e32 v92, v81, v80
	v_mul_f32_e32 v88, v89, v88
	v_cvt_pk_bf16_f32 v80, v91, v84
	v_cvt_pk_bf16_f32 v81, v85, v86
	v_cvt_pk_bf16_f32 v82, v87, v92
	v_cvt_pk_bf16_f32 v83, v88, v83
	global_store_dwordx4 v[98:99], v[80:83], off
	s_nop 0
	s_nop 0
	v_mov_b32_e32 v80, v76
	v_mov_b32_e32 v76, v78
	v_mov_b32_e32 v78, v72
	v_mov_b32_e32 v72, v74
	v_mov_b32_e32 v81, v68
	v_mov_b32_e32 v68, v77
	v_mov_b32_e32 v77, v70
	v_mov_b32_e32 v70, v79
	v_mov_b32_e32 v79, v64
	v_mov_b32_e32 v64, v73
	v_mov_b32_e32 v73, v66
	v_mov_b32_e32 v66, v75
	s_nop 0
	v_fmamk_f32 v74, v235, 0x3a800000, v154
	v_mul_f32_e32 v75, 0x4b800000, v74
	v_cmp_gt_f32_e32 vcc, s54, v74
	s_nop 1
	v_cndmask_b32_e32 v74, v74, v75, vcc
	v_rsq_f32_e32 v82, v74
	v_mad_i64_i32 v[74:75], s[0:1], v90, s55, v[120:121]
	v_lshl_add_u64 v[74:75], v[74:75], 0, v[122:123]
	v_mul_f32_e32 v83, 0x45800000, v82
	v_cndmask_b32_e32 v82, v82, v83, vcc
	v_pk_mul_f32 v[66:67], v[66:67], v[82:83] op_sel_hi:[1,0]
	v_pk_mul_f32 v[80:81], v[80:81], v[82:83] op_sel_hi:[1,0]
	v_pk_mul_f32 v[68:69], v[68:69], v[82:83] op_sel_hi:[1,0]
	v_pk_mul_f32 v[76:77], v[76:77], v[82:83] op_sel_hi:[1,0]
	v_pk_mul_f32 v[70:71], v[70:71], v[82:83] op_sel_hi:[1,0]
	v_pk_mul_f32 v[78:79], v[78:79], v[82:83] op_sel_hi:[1,0]
	v_pk_mul_f32 v[64:65], v[64:65], v[82:83] op_sel_hi:[1,0]
	v_pk_mul_f32 v[72:73], v[72:73], v[82:83] op_sel_hi:[1,0]
	v_mul_f32_e32 v67, v66, v67
	v_mul_f32_e32 v66, 0xbfb8aa3b, v66
	v_mul_f32_e32 v81, v80, v81
	v_mul_f32_e32 v80, 0xbfb8aa3b, v80
	v_mul_f32_e32 v69, v68, v69
	v_mul_f32_e32 v68, 0xbfb8aa3b, v68
	v_mul_f32_e32 v77, v76, v77
	v_mul_f32_e32 v76, 0xbfb8aa3b, v76
	v_mul_f32_e32 v71, v70, v71
	v_mul_f32_e32 v70, 0xbfb8aa3b, v70
	v_mul_f32_e32 v79, v78, v79
	v_mul_f32_e32 v78, 0xbfb8aa3b, v78
	v_mul_f32_e32 v65, v64, v65
	v_mul_f32_e32 v64, 0xbfb8aa3b, v64
	v_mul_f32_e32 v73, v72, v73
	v_mul_f32_e32 v72, 0xbfb8aa3b, v72
	v_exp_f32_e32 v66, v66
	v_exp_f32_e32 v80, v80
	v_exp_f32_e32 v68, v68
	v_exp_f32_e32 v76, v76
	v_exp_f32_e32 v70, v70
	v_exp_f32_e32 v78, v78
	v_exp_f32_e32 v64, v64
	v_exp_f32_e32 v72, v72
	v_add_f32_e32 v66, 1.0, v66
	v_add_f32_e32 v80, 1.0, v80
	v_add_f32_e32 v68, 1.0, v68
	v_add_f32_e32 v76, 1.0, v76
	v_add_f32_e32 v70, 1.0, v70
	v_add_f32_e32 v78, 1.0, v78
	v_add_f32_e32 v64, 1.0, v64
	v_add_f32_e32 v72, 1.0, v72
	v_rcp_f32_e32 v66, v66
	v_rcp_f32_e32 v80, v80
	v_rcp_f32_e32 v68, v68
	v_rcp_f32_e32 v76, v76
	v_rcp_f32_e32 v70, v70
; __device__ __forceinline__ float sigmoidf_(float x) { return __builtin_amdgcn_rcpf(1.f + __expf(-x)); }
;     __device__ __forceinline__ void operator()(const AccT& acc, const Unit& u, int wr, int wc, int fr, int fq) const {
;     ...
;             for (int m = 0; m < 4; ++m) {
;                 const int row = row0 + ai * HALF + m * 16;
;                 const float rs = rsqrtf(ss[row] * (1.f / 1024.f) + EPS);
;                 float o[8];
; #pragma unroll
;                 for (int n = 0; n < 2; ++n)
; #pragma unroll
;                     for (int j = 0; j < 4; ++j) { const float gt = acc[ai][0][m][n][j] * rs, up = acc[ai][1][m][n][j] * rs; o[n * 4 + j] = gt * up * sigmoidf_(gt); }
;                 *(u32x4*)(O + (size_t)row * FF + col) = pack8(o);
	v_rcp_f32_e32 v78, v78
	v_rcp_f32_e32 v64, v64
	v_rcp_f32_e32 v72, v72
	v_mul_f32_e32 v67, v67, v66
	v_mul_f32_e32 v80, v81, v80
	v_mul_f32_e32 v68, v69, v68
	v_mul_f32_e32 v69, v77, v76
	v_mul_f32_e32 v70, v71, v70
	v_mul_f32_e32 v71, v79, v78
	v_mul_f32_e32 v76, v65, v64
	v_mul_f32_e32 v72, v73, v72
	v_cvt_pk_bf16_f32 v64, v80, v68
	v_cvt_pk_bf16_f32 v65, v69, v70
	v_cvt_pk_bf16_f32 v66, v71, v76
	v_cvt_pk_bf16_f32 v67, v72, v67
	global_store_dwordx4 v[74:75], v[64:67], off
	s_nop 0
	s_nop 0
	v_mov_b32_e32 v65, v52
	v_mov_b32_e32 v52, v61
	v_mov_b32_e32 v61, v54
	v_mov_b32_e32 v54, v63
	v_mov_b32_e32 v63, v48
	v_mov_b32_e32 v48, v57
	v_mov_b32_e32 v57, v50
	v_mov_b32_e32 v50, v59
	v_mov_b32_e32 v64, v60
	v_mov_b32_e32 v60, v62
	v_mov_b32_e32 v62, v56
	v_mov_b32_e32 v56, v58
	v_add_u32_e32 v58, 0x80, v144
	s_nop 0
	v_fmamk_f32 v59, v236, 0x3a800000, v154
	v_mul_f32_e32 v66, 0x4b800000, v59
	v_cmp_gt_f32_e32 vcc, s54, v59
	s_nop 1
	v_cndmask_b32_e32 v59, v59, v66, vcc
	v_rsq_f32_e32 v66, v59
	v_mad_i64_i32 v[58:59], s[0:1], v58, s55, v[120:121]
	v_lshl_add_u64 v[58:59], v[58:59], 0, v[122:123]
	v_mul_f32_e32 v67, 0x45800000, v66
	v_cndmask_b32_e32 v66, v66, v67, vcc
	v_pk_mul_f32 v[50:51], v[50:51], v[66:67] op_sel_hi:[1,0]
	v_pk_mul_f32 v[64:65], v[64:65], v[66:67] op_sel_hi:[1,0]
	v_pk_mul_f32 v[52:53], v[52:53], v[66:67] op_sel_hi:[1,0]
	v_pk_mul_f32 v[60:61], v[60:61], v[66:67] op_sel_hi:[1,0]
	v_pk_mul_f32 v[54:55], v[54:55], v[66:67] op_sel_hi:[1,0]
	v_pk_mul_f32 v[62:63], v[62:63], v[66:67] op_sel_hi:[1,0]
	v_pk_mul_f32 v[48:49], v[48:49], v[66:67] op_sel_hi:[1,0]
	v_pk_mul_f32 v[56:57], v[56:57], v[66:67] op_sel_hi:[1,0]
	v_mul_f32_e32 v51, v50, v51
	v_mul_f32_e32 v50, 0xbfb8aa3b, v50
	v_mul_f32_e32 v65, v64, v65
	v_mul_f32_e32 v64, 0xbfb8aa3b, v64
	v_mul_f32_e32 v53, v52, v53
	v_mul_f32_e32 v52, 0xbfb8aa3b, v52
	v_mul_f32_e32 v61, v60, v61
	v_mul_f32_e32 v60, 0xbfb8aa3b, v60
	v_mul_f32_e32 v55, v54, v55
	v_mul_f32_e32 v54, 0xbfb8aa3b, v54
	v_mul_f32_e32 v63, v62, v63
	v_mul_f32_e32 v62, 0xbfb8aa3b, v62
	v_mul_f32_e32 v49, v48, v49
	v_mul_f32_e32 v48, 0xbfb8aa3b, v48
	v_mul_f32_e32 v57, v56, v57
	v_mul_f32_e32 v56, 0xbfb8aa3b, v56
	v_exp_f32_e32 v50, v50
	v_exp_f32_e32 v64, v64
	v_exp_f32_e32 v52, v52
	v_exp_f32_e32 v60, v60
	v_exp_f32_e32 v54, v54
	v_exp_f32_e32 v62, v62
	v_exp_f32_e32 v48, v48
	v_exp_f32_e32 v56, v56
	v_add_f32_e32 v50, 1.0, v50
	v_add_f32_e32 v64, 1.0, v64
	v_add_f32_e32 v52, 1.0, v52
	v_add_f32_e32 v60, 1.0, v60
	v_add_f32_e32 v54, 1.0, v54
	v_add_f32_e32 v62, 1.0, v62
	v_add_f32_e32 v48, 1.0, v48
	v_add_f32_e32 v56, 1.0, v56
	v_rcp_f32_e32 v50, v50
	v_rcp_f32_e32 v64, v64
	v_rcp_f32_e32 v52, v52
	v_rcp_f32_e32 v60, v60
	v_rcp_f32_e32 v54, v54
	v_rcp_f32_e32 v62, v62
	v_rcp_f32_e32 v48, v48
	v_rcp_f32_e32 v56, v56
	v_mul_f32_e32 v51, v51, v50
	v_mul_f32_e32 v64, v65, v64
	v_mul_f32_e32 v52, v53, v52
	v_mul_f32_e32 v53, v61, v60
	v_mul_f32_e32 v54, v55, v54
	v_mul_f32_e32 v55, v63, v62
	v_mul_f32_e32 v60, v49, v48
	v_mul_f32_e32 v56, v57, v56
	v_cvt_pk_bf16_f32 v48, v64, v52
	v_cvt_pk_bf16_f32 v49, v53, v54
	v_cvt_pk_bf16_f32 v50, v55, v60
	v_cvt_pk_bf16_f32 v51, v56, v51
	global_store_dwordx4 v[58:59], v[48:51], off
	s_nop 0
	s_nop 0
	v_mov_b32_e32 v49, v36
	v_mov_b32_e32 v36, v45
	v_mov_b32_e32 v45, v38
	v_mov_b32_e32 v38, v47
	v_mov_b32_e32 v47, v32
	v_mov_b32_e32 v32, v41
	v_mov_b32_e32 v41, v34
	v_mov_b32_e32 v34, v43
	v_mov_b32_e32 v48, v44
	v_mov_b32_e32 v44, v46
	v_mov_b32_e32 v46, v40
	v_mov_b32_e32 v40, v42
	v_add_u32_e32 v42, 0x90, v144
	s_nop 0
	v_fmamk_f32 v43, v237, 0x3a800000, v154
	v_mul_f32_e32 v50, 0x4b800000, v43
	v_cmp_gt_f32_e32 vcc, s54, v43
	s_nop 1
	v_cndmask_b32_e32 v43, v43, v50, vcc
	v_rsq_f32_e32 v50, v43
	v_mad_i64_i32 v[42:43], s[0:1], v42, s55, v[120:121]
	v_lshl_add_u64 v[42:43], v[42:43], 0, v[122:123]
	v_mul_f32_e32 v51, 0x45800000, v50
	v_cndmask_b32_e32 v50, v50, v51, vcc
	v_pk_mul_f32 v[34:35], v[34:35], v[50:51] op_sel_hi:[1,0]
	v_pk_mul_f32 v[48:49], v[48:49], v[50:51] op_sel_hi:[1,0]
	v_pk_mul_f32 v[36:37], v[36:37], v[50:51] op_sel_hi:[1,0]
	v_pk_mul_f32 v[44:45], v[44:45], v[50:51] op_sel_hi:[1,0]
	v_pk_mul_f32 v[38:39], v[38:39], v[50:51] op_sel_hi:[1,0]
	v_pk_mul_f32 v[46:47], v[46:47], v[50:51] op_sel_hi:[1,0]
	v_pk_mul_f32 v[32:33], v[32:33], v[50:51] op_sel_hi:[1,0]
	v_pk_mul_f32 v[40:41], v[40:41], v[50:51] op_sel_hi:[1,0]
	v_mul_f32_e32 v35, v34, v35
	v_mul_f32_e32 v34, 0xbfb8aa3b, v34
	v_mul_f32_e32 v49, v48, v49
	v_mul_f32_e32 v48, 0xbfb8aa3b, v48
	v_mul_f32_e32 v37, v36, v37
	v_mul_f32_e32 v36, 0xbfb8aa3b, v36
	v_mul_f32_e32 v45, v44, v45
	v_mul_f32_e32 v44, 0xbfb8aa3b, v44
	v_mul_f32_e32 v39, v38, v39
	v_mul_f32_e32 v38, 0xbfb8aa3b, v38
	v_mul_f32_e32 v47, v46, v47
	v_mul_f32_e32 v46, 0xbfb8aa3b, v46
	v_mul_f32_e32 v33, v32, v33
	v_mul_f32_e32 v32, 0xbfb8aa3b, v32
	v_mul_f32_e32 v41, v40, v41
	v_mul_f32_e32 v40, 0xbfb8aa3b, v40
	v_exp_f32_e32 v34, v34
	v_exp_f32_e32 v48, v48
	v_exp_f32_e32 v36, v36
	v_exp_f32_e32 v44, v44
	v_exp_f32_e32 v38, v38
	v_exp_f32_e32 v46, v46
	v_exp_f32_e32 v32, v32
	v_exp_f32_e32 v40, v40
	v_add_f32_e32 v34, 1.0, v34
	v_add_f32_e32 v48, 1.0, v48
	v_add_f32_e32 v36, 1.0, v36
	v_add_f32_e32 v44, 1.0, v44
	v_add_f32_e32 v38, 1.0, v38
	v_add_f32_e32 v46, 1.0, v46
	v_add_f32_e32 v32, 1.0, v32
	v_add_f32_e32 v40, 1.0, v40
	v_rcp_f32_e32 v34, v34
	v_rcp_f32_e32 v48, v48
	v_rcp_f32_e32 v36, v36
	v_rcp_f32_e32 v44, v44
	v_rcp_f32_e32 v38, v38
	v_rcp_f32_e32 v46, v46
	v_rcp_f32_e32 v32, v32
	v_rcp_f32_e32 v40, v40
	v_mul_f32_e32 v35, v35, v34
	v_mul_f32_e32 v48, v49, v48
	v_mul_f32_e32 v36, v37, v36
	v_mul_f32_e32 v37, v45, v44
; __device__ __forceinline__ float sigmoidf_(float x) { return __builtin_amdgcn_rcpf(1.f + __expf(-x)); }
; #define PG8_BAR __builtin_amdgcn_s_barrier()
; template <class Epi>
; __device__ __forceinline__ void gemm_phase(LAS unsigned char* lds, const Gemm g, const StaticOrder& S, const Epi& E) {
;     ...
;         if (wr == 0) PG8_BAR;
;         E(acc, cur, wr, wc, fr, fq);
;         if (!has_next) break;
; #pragma unroll
;         for (int a = 0; a < 2; ++a)
; #pragma unroll
;             for (int b = 0; b < 2; ++b)
; #pragma unroll
;                 for (int m = 0; m < 4; ++m)
; #pragma unroll
;                     for (int n = 0; n < 2; ++n) acc[a][b][m][n] = (f32x4){0.f, 0.f, 0.f, 0.f};
;         cur = nxt; cA = nA; cB = nB; ++ui;
;         if (wr == 1) PG8_BAR;
;     __device__ __forceinline__ void operator()(const AccT& acc, const Unit& u, int wr, int wc, int fr, int fq) const {
;     ...
;             for (int m = 0; m < 4; ++m) {
;                 const int row = row0 + ai * HALF + m * 16;
;                 const float rs = rsqrtf(ss[row] * (1.f / 1024.f) + EPS);
;                 float o[8];
; #pragma unroll
;                 for (int n = 0; n < 2; ++n)
; #pragma unroll
;                     for (int j = 0; j < 4; ++j) { const float gt = acc[ai][0][m][n][j] * rs, up = acc[ai][1][m][n][j] * rs; o[n * 4 + j] = gt * up * sigmoidf_(gt); }
;                 *(u32x4*)(O + (size_t)row * FF + col) = pack8(o);
	v_mul_f32_e32 v38, v39, v38
	v_mul_f32_e32 v39, v47, v46
	v_mul_f32_e32 v44, v33, v32
	v_mul_f32_e32 v40, v41, v40
	v_cvt_pk_bf16_f32 v32, v48, v36
	v_cvt_pk_bf16_f32 v33, v37, v38
	v_cvt_pk_bf16_f32 v34, v39, v44
	v_cvt_pk_bf16_f32 v35, v40, v35
	global_store_dwordx4 v[42:43], v[32:35], off
	s_nop 0
	s_nop 0
	v_mov_b32_e32 v33, v20
	v_mov_b32_e32 v20, v29
	v_mov_b32_e32 v29, v22
	v_mov_b32_e32 v22, v31
	v_mov_b32_e32 v31, v16
	v_mov_b32_e32 v16, v25
	v_mov_b32_e32 v25, v18
	v_mov_b32_e32 v18, v27
	v_mov_b32_e32 v32, v28
	v_mov_b32_e32 v28, v30
	v_mov_b32_e32 v30, v24
	v_mov_b32_e32 v24, v26
	v_add_u32_e32 v26, 0xa0, v144
	s_nop 0
	v_fmamk_f32 v27, v238, 0x3a800000, v154
	v_mul_f32_e32 v34, 0x4b800000, v27
	v_cmp_gt_f32_e32 vcc, s54, v27
	s_nop 1
	v_cndmask_b32_e32 v27, v27, v34, vcc
	v_rsq_f32_e32 v34, v27
	v_mad_i64_i32 v[26:27], s[0:1], v26, s55, v[120:121]
	v_lshl_add_u64 v[26:27], v[26:27], 0, v[122:123]
	v_mul_f32_e32 v35, 0x45800000, v34
	v_cndmask_b32_e32 v34, v34, v35, vcc
	v_pk_mul_f32 v[18:19], v[18:19], v[34:35] op_sel_hi:[1,0]
	v_pk_mul_f32 v[32:33], v[32:33], v[34:35] op_sel_hi:[1,0]
	v_pk_mul_f32 v[20:21], v[20:21], v[34:35] op_sel_hi:[1,0]
	v_pk_mul_f32 v[28:29], v[28:29], v[34:35] op_sel_hi:[1,0]
	v_pk_mul_f32 v[22:23], v[22:23], v[34:35] op_sel_hi:[1,0]
	v_pk_mul_f32 v[30:31], v[30:31], v[34:35] op_sel_hi:[1,0]
	v_pk_mul_f32 v[16:17], v[16:17], v[34:35] op_sel_hi:[1,0]
	v_pk_mul_f32 v[24:25], v[24:25], v[34:35] op_sel_hi:[1,0]
	v_mul_f32_e32 v19, v18, v19
	v_mul_f32_e32 v18, 0xbfb8aa3b, v18
	v_mul_f32_e32 v33, v32, v33
	v_mul_f32_e32 v32, 0xbfb8aa3b, v32
	v_mul_f32_e32 v21, v20, v21
	v_mul_f32_e32 v20, 0xbfb8aa3b, v20
	v_mul_f32_e32 v29, v28, v29
	v_mul_f32_e32 v28, 0xbfb8aa3b, v28
	v_mul_f32_e32 v23, v22, v23
	v_mul_f32_e32 v22, 0xbfb8aa3b, v22
	v_mul_f32_e32 v31, v30, v31
	v_mul_f32_e32 v30, 0xbfb8aa3b, v30
	v_mul_f32_e32 v17, v16, v17
	v_mul_f32_e32 v16, 0xbfb8aa3b, v16
	v_mul_f32_e32 v25, v24, v25
	v_mul_f32_e32 v24, 0xbfb8aa3b, v24
	v_exp_f32_e32 v18, v18
	v_exp_f32_e32 v32, v32
	v_exp_f32_e32 v20, v20
	v_exp_f32_e32 v28, v28
	v_exp_f32_e32 v22, v22
	v_exp_f32_e32 v30, v30
	v_exp_f32_e32 v16, v16
	v_exp_f32_e32 v24, v24
	v_add_f32_e32 v18, 1.0, v18
	v_add_f32_e32 v32, 1.0, v32
	v_add_f32_e32 v20, 1.0, v20
	v_add_f32_e32 v28, 1.0, v28
	v_add_f32_e32 v22, 1.0, v22
	v_add_f32_e32 v30, 1.0, v30
	v_add_f32_e32 v16, 1.0, v16
	v_add_f32_e32 v24, 1.0, v24
	v_rcp_f32_e32 v18, v18
	v_rcp_f32_e32 v32, v32
	v_rcp_f32_e32 v20, v20
	v_rcp_f32_e32 v28, v28
	v_rcp_f32_e32 v22, v22
	v_rcp_f32_e32 v30, v30
	v_rcp_f32_e32 v16, v16
	v_rcp_f32_e32 v24, v24
	v_mul_f32_e32 v19, v19, v18
	v_mul_f32_e32 v32, v33, v32
	v_mul_f32_e32 v20, v21, v20
	v_mul_f32_e32 v21, v29, v28
	v_mul_f32_e32 v22, v23, v22
	v_mul_f32_e32 v23, v31, v30
	v_mul_f32_e32 v28, v17, v16
	v_mul_f32_e32 v24, v25, v24
	v_cvt_pk_bf16_f32 v16, v32, v20
	v_cvt_pk_bf16_f32 v17, v21, v22
	v_cvt_pk_bf16_f32 v18, v23, v28
	v_cvt_pk_bf16_f32 v19, v24, v19
	global_store_dwordx4 v[26:27], v[16:19], off
	s_nop 0
	s_andn2_b64 vcc, exec, s[4:5]
	v_mov_b32_e32 v17, v4
	v_mov_b32_e32 v4, v13
	v_mov_b32_e32 v13, v6
	v_mov_b32_e32 v6, v15
	v_mov_b32_e32 v15, v0
	v_mov_b32_e32 v0, v9
	v_mov_b32_e32 v9, v2
	v_mov_b32_e32 v2, v11
	v_mov_b32_e32 v16, v12
	v_mov_b32_e32 v12, v14
	v_mov_b32_e32 v14, v8
	v_mov_b32_e32 v8, v10
	v_add_u32_e32 v10, 0xb0, v144
	s_nop 0
	v_fmamk_f32 v11, v239, 0x3a800000, v154
	v_mul_f32_e32 v18, 0x4b800000, v11
	v_cmp_gt_f32_e64 s[0:1], s54, v11
	s_nop 1
	v_cndmask_b32_e64 v11, v11, v18, s[0:1]
	v_rsq_f32_e32 v18, v11
	v_mad_i64_i32 v[10:11], s[22:23], v10, s55, v[120:121]
	v_lshl_add_u64 v[10:11], v[10:11], 0, v[122:123]
	v_mul_f32_e32 v19, 0x45800000, v18
	v_cndmask_b32_e64 v18, v18, v19, s[0:1]
	v_pk_mul_f32 v[2:3], v[2:3], v[18:19] op_sel_hi:[1,0]
	v_pk_mul_f32 v[16:17], v[16:17], v[18:19] op_sel_hi:[1,0]
	v_pk_mul_f32 v[4:5], v[4:5], v[18:19] op_sel_hi:[1,0]
	v_pk_mul_f32 v[12:13], v[12:13], v[18:19] op_sel_hi:[1,0]
	v_pk_mul_f32 v[6:7], v[6:7], v[18:19] op_sel_hi:[1,0]
	v_pk_mul_f32 v[14:15], v[14:15], v[18:19] op_sel_hi:[1,0]
	v_pk_mul_f32 v[0:1], v[0:1], v[18:19] op_sel_hi:[1,0]
	v_pk_mul_f32 v[8:9], v[8:9], v[18:19] op_sel_hi:[1,0]
	v_mul_f32_e32 v3, v2, v3
	v_mul_f32_e32 v2, 0xbfb8aa3b, v2
	v_mul_f32_e32 v17, v16, v17
	v_mul_f32_e32 v16, 0xbfb8aa3b, v16
	v_mul_f32_e32 v5, v4, v5
	v_mul_f32_e32 v4, 0xbfb8aa3b, v4
	v_mul_f32_e32 v13, v12, v13
	v_mul_f32_e32 v12, 0xbfb8aa3b, v12
	v_mul_f32_e32 v7, v6, v7
	v_mul_f32_e32 v6, 0xbfb8aa3b, v6
	v_mul_f32_e32 v15, v14, v15
	v_mul_f32_e32 v14, 0xbfb8aa3b, v14
	v_mul_f32_e32 v1, v0, v1
	v_mul_f32_e32 v0, 0xbfb8aa3b, v0
	v_mul_f32_e32 v9, v8, v9
	v_mul_f32_e32 v8, 0xbfb8aa3b, v8
	v_exp_f32_e32 v2, v2
	v_exp_f32_e32 v16, v16
	v_exp_f32_e32 v4, v4
	v_exp_f32_e32 v12, v12
	v_exp_f32_e32 v6, v6
	v_exp_f32_e32 v14, v14
	v_exp_f32_e32 v0, v0
	v_exp_f32_e32 v8, v8
	v_add_f32_e32 v2, 1.0, v2
	v_add_f32_e32 v16, 1.0, v16
	v_add_f32_e32 v4, 1.0, v4
	v_add_f32_e32 v12, 1.0, v12
	v_add_f32_e32 v6, 1.0, v6
	v_add_f32_e32 v14, 1.0, v14
	v_add_f32_e32 v0, 1.0, v0
	v_add_f32_e32 v8, 1.0, v8
	v_rcp_f32_e32 v2, v2
	v_rcp_f32_e32 v16, v16
	v_rcp_f32_e32 v4, v4
	v_rcp_f32_e32 v12, v12
	v_rcp_f32_e32 v6, v6
	v_rcp_f32_e32 v14, v14
	v_rcp_f32_e32 v0, v0
	v_rcp_f32_e32 v8, v8
	v_mul_f32_e32 v3, v3, v2
	s_mov_b64 s[0:1], -1
	v_mul_f32_e32 v16, v17, v16
	v_mul_f32_e32 v4, v5, v4
	v_mul_f32_e32 v5, v13, v12
	v_mul_f32_e32 v6, v7, v6
	v_mul_f32_e32 v7, v15, v14
	v_mul_f32_e32 v12, v1, v0
	v_mul_f32_e32 v8, v9, v8
	v_cvt_pk_bf16_f32 v0, v16, v4
	v_cvt_pk_bf16_f32 v1, v5, v6
	v_cvt_pk_bf16_f32 v2, v7, v12
	v_cvt_pk_bf16_f32 v3, v8, v3
	global_store_dwordx4 v[10:11], v[0:3], off
	s_cbranch_vccnz .LBB0_1554
	s_andn2_b64 vcc, exec, s[6:7]
	s_cbranch_vccnz .LBB0_1553
	s_barrier
	s_branch .LBB0_1553
